# adds: per-row rstd cached in registers across consecutive tiles of the same row block (in-proj, gates epilogues)
# baseline (speedup 1.0000x reference)
; __device__ __forceinline__ int fresh_tid() { int t = threadIdx.x; asm volatile("" : "+v"(t)); return t; }
; #define PG8_STAGE(bufoff, gbase, voff) do { _Pragma("unroll") for (int _i = 0; _i < 2; ++_i) \
;         __builtin_amdgcn_global_load_lds((const unsigned*)((const char*)(gbase) + (voff)[_i]), (LAS unsigned*)(lds + (bufoff) + ldsw + _i * 8192), 16, 0, 0); } while (0)
; #define PG8_WAIT_V(n) asm volatile("s_waitcnt vmcnt(" #n ")" ::: "memory")
; template <class Epi, class Sched, int NSEG, int KK, int LDA, int LDB>
; __device__ __forceinline__ void gemm_phase(LAS unsigned char* lds, const Gemm g, const Sched& S, const Epi& E) {
;     const int tid = fresh_tid(), wid = __builtin_amdgcn_readfirstlane(tid >> 6), lane = tid & 63, wr = wid >> 2, wc = wid & 3, fr = lane & 15, fq = lane >> 4;
;     constexpr int nt = KK / BK;
;     unsigned voffA[2], voffB[2];
; #pragma unroll
;     for (int i = 0; i < 2; ++i) { int R, C; stage_rc(tid * 16 + i * 8192, R, C); const int Rb = Epi::PERM ? ((R & ~31) + perm32(R & 31)) : R;
;         voffA[i] = (unsigned)(R * LDA + C) * 2u; voffB[i] = (unsigned)(Rb * LDB + C) * 2u; }
;     constexpr size_t kstep = (size_t)(BK * 2);
;     constexpr size_t hstepA = (size_t)HALF * LDA * 2, hstepB = (size_t)HALF * LDB * 2;
;     constexpr size_t tstepA = 2 * hstepA, tstepB = 2 * hstepB;
;     const unsigned ldsw = (unsigned)wid * 1024u;
;     const int aoff = lds_byte(wr * 64 + fr, fq * 8), boff = lds_byte(wc * 32 + fr, fq * 8);
;     ...
;     Unit cur, nxt; int ui = 0;
;     if (!S.next(0, cur)) return;
;     f32x4 acc[2][2][4][2];
; #pragma unroll
;     for (int a = 0; a < 2; ++a)
; #pragma unroll
;         for (int b = 0; b < 2; ++b)
; #pragma unroll
;             for (int m = 0; m < 4; ++m)
; #pragma unroll
;                 for (int n = 0; n < 2; ++n) acc[a][b][m][n] = (f32x4){0.f, 0.f, 0.f, 0.f};
;     bf16x8 At[4][2], B0[2][2], B1[2][2];
;     const char* cA = PG8_APTR(cur); const char* cB = PG8_BPTR(cur);
;     PG8_STAGE(PG8_SB(0, 0), cB, voffB); PG8_STAGE(PG8_SB(0, 1), cB + hstepB, voffB); PG8_STAGE(PG8_SA(0, 0), cA, voffA); PG8_STAGE(PG8_SA(0, 1), cA + hstepA, voffA);
;     if (wr == 1) PG8_BAR;
;     PG8_WAIT_V(2); PG8_BAR;
;     PG8_STAGE(PG8_SB(1, 0), cB + kstep, voffB); PG8_STAGE(PG8_SA(1, 0), cA + kstep, voffA); PG8_STAGE(PG8_SB(1, 1), cB + hstepB + kstep, voffB);
;     PG8_WAIT_V(6); PG8_BAR;
.LBB0_379:
	s_mov_b32 s101, 0
	s_mov_b32 s100, -1
	s_mul_i32 s8, s94, 0x2480000
	s_add_u32 s8, s88, s8
	v_writelane_b32 v254, s8, 22
	s_addc_u32 s8, s89, 0
	v_writelane_b32 v254, s8, 23
	v_readlane_b32 s8, v253, 40
	v_mov_b32_e32 v2, v246
	v_readlane_b32 s9, v253, 41
	s_andn2_b64 vcc, exec, s[8:9]
	v_readfirstlane_b32 s24, v2
	s_cbranch_vccnz .LBB0_427
	v_lshlrev_b32_e32 v5, 4, v2
	v_add_u32_e32 v3, 0x2000, v5
	v_ashrrev_i32_e32 v0, 31, v3
	v_lshrrev_b32_e32 v0, 22, v0
	v_add_u32_e32 v0, v3, v0
	v_ashrrev_i32_e32 v0, 10, v0
	v_mul_i32_i24_e32 v4, 0x400, v0
	v_sub_u32_e32 v3, v3, v4
	v_lshrrev_b32_e32 v4, 4, v3
	v_bitop3_b32 v4, v4, v3, 32 bitop3:0x6c
	v_ashrrev_i32_e32 v3, 31, v4
	v_lshrrev_b32_e32 v3, 26, v3
	v_add_u32_e32 v6, v4, v3
	v_lshlrev_b32_e32 v7, 3, v0
	v_ashrrev_i32_e32 v3, 6, v6
	v_and_b32_e32 v7, -16, v7
	v_add_u32_e32 v7, v3, v7
	v_and_b32_e32 v8, 3, v3
	s_mov_b32 s8, 0x1fffe0
	v_lshrrev_b32_e32 v9, 2, v7
	v_lshlrev_b32_e32 v10, 1, v7
	v_and_b32_e32 v6, 0xc0, v6
	v_and_or_b32 v8, v7, s8, v8
	v_and_b32_e32 v9, 4, v9
	v_and_b32_e32 v10, 24, v10
	v_sub_u32_e32 v4, v4, v6
	v_or3_b32 v8, v8, v9, v10
	v_lshlrev_b32_e32 v9, 5, v0
	v_ashrrev_i16_sdwa v4, v248, sext(v4) dst_sel:DWORD dst_unused:UNUSED_PAD src0_sel:DWORD src1_sel:BYTE_0
	v_and_b32_e32 v9, 32, v9
	v_bfe_i32 v4, v4, 0, 16
	v_add_lshl_u32 v6, v9, v4, 1
	v_lshl_add_u32 v142, v8, 11, v6
	v_lshl_add_u32 v144, v7, 11, v6
	v_bfe_i32 v6, v2, 27, 1
	v_lshrrev_b32_e32 v6, 22, v6
	v_add_u32_e32 v6, v5, v6
	v_and_b32_e32 v6, 0xfffffc00, v6
	v_sub_u32_e32 v5, v5, v6
	v_lshrrev_b32_e32 v6, 4, v5
	v_bitop3_b32 v7, v6, v5, 32 bitop3:0x6c
	v_ashrrev_i32_e32 v6, 31, v2
	v_lshrrev_b32_e32 v6, 26, v6
	v_ashrrev_i32_e32 v5, 31, v5
	v_add_u32_e32 v6, v2, v6
	v_lshrrev_b32_e32 v5, 26, v5
	v_ashrrev_i32_e32 v6, 6, v6
	v_add_u32_e32 v5, v7, v5
	v_lshlrev_b32_e32 v8, 3, v6
	v_ashrrev_i32_e32 v5, 6, v5
	v_and_b32_e32 v8, -16, v8
	v_add_u32_e32 v8, v5, v8
	v_and_b32_e32 v9, 3, v5
	v_lshrrev_b32_e32 v10, 2, v8
	v_lshlrev_b32_e32 v11, 1, v8
	v_and_or_b32 v9, v8, s8, v9
	v_and_b32_e32 v10, 4, v10
	v_and_b32_e32 v11, 24, v11
	v_or3_b32 v9, v9, v10, v11
	v_mul_i32_i24_e32 v11, 64, v5
	s_ashr_i32 s25, s24, 6
	v_sub_u32_e32 v7, v7, v11
	s_ashr_i32 s12, s24, 8
	s_lshl_b32 s13, s25, 10
	v_lshlrev_b32_e32 v10, 5, v6
	v_ashrrev_i16_sdwa v7, v248, sext(v7) dst_sel:DWORD dst_unused:UNUSED_PAD src0_sel:DWORD src1_sel:BYTE_0
	v_readlane_b32 s8, v255, 36
	v_readlane_b32 s10, v254, 22
	v_and_b32_e32 v10, 32, v10
	v_bfe_i32 v7, v7, 0, 16
	v_readlane_b32 s9, v255, 37
	s_add_u32 s10, s10, s8
	v_readlane_b32 s8, v254, 23
	v_add_lshl_u32 v10, v10, v7, 1
	s_addc_u32 s11, s8, s9
	s_add_i32 s22, s13, 0
	v_lshl_add_u32 v146, v9, 11, v10
	s_add_i32 m0, s22, 0x10000
	v_lshl_add_u32 v148, v8, 11, v10
	global_load_lds_dwordx4 v146, s[10:11]
	s_add_i32 m0, s22, 0x12000
	s_add_u32 s8, s10, 0x40000
	global_load_lds_dwordx4 v142, s[10:11]
	s_addc_u32 s9, s11, 0
	s_add_i32 m0, s22, 0x14000
	s_add_i32 s23, s22, 0x2000
	global_load_lds_dwordx4 v146, s[8:9]
	s_add_i32 m0, s22, 0x16000
	s_add_i32 s26, s22, 0x4000
	global_load_lds_dwordx4 v142, s[8:9]
	v_readlane_b32 s8, v255, 40
	s_mov_b32 m0, s22
	v_readlane_b32 s9, v255, 41
	s_add_i32 s33, s22, 0x6000
	s_cmp_eq_u32 s12, 1
	s_nop 2
	global_load_lds_dwordx4 v148, s[8:9]
	s_mov_b32 m0, s23
	s_nop 0
	global_load_lds_dwordx4 v144, s[8:9]
	v_readlane_b32 s8, v255, 42
	s_mov_b32 m0, s26
	v_readlane_b32 s9, v255, 43
	s_nop 4
	global_load_lds_dwordx4 v148, s[8:9]
	s_mov_b32 m0, s33
	s_nop 0
	global_load_lds_dwordx4 v144, s[8:9]
	s_cselect_b64 s[8:9], -1, 0
	s_cmp_lg_u32 s12, 1
	s_cbranch_scc1 .LBB0_382
	s_barrier

; __device__ __forceinline__ unsigned cvt_pk_bf16(float lo, float hi) { unsigned r; asm volatile("s_nop 1\n\tv_cvt_pk_bf16_f32 %0, %1, %2" : "=v"(r) : "v"(lo), "v"(hi)); return r; }
;     f32x4 p[2][4];
; #pragma unroll
;     for (int ai = 0; ai < 2; ++ai)
; #pragma unroll
;         for (int m = 0; m < 4; ++m) { const size_t r = (size_t)(u.pm * BM + ai * HALF + wr * 64 + m * 16 + fr); p[ai][m] = *(const f32x4*)(ssq + ((size_t)fq * T + r) * 4); }
; #pragma unroll
;     for (int ai = 0; ai < 2; ++ai)
; #pragma unroll
;         for (int m = 0; m < 4; ++m) { float sq = (p[ai][m].x + p[ai][m].y) + (p[ai][m].z + p[ai][m].w);
;             sq += __shfl_xor(sq, 16); sq += __shfl_xor(sq, 32);
;             const float rs = __builtin_amdgcn_rsqf(sq * (1.0f / DM) + EPS) * mul;
; #pragma unroll
;             for (int bj = 0; bj < 2; ++bj)
; #pragma unroll
;                 for (int n = 0; n < 2; ++n) acc[ai][bj][m][n] = acc[ai][bj][m][n] * rs; }
; }
;     __device__ __forceinline__ void operator()(f32x4 (&acc)[2][2][4][2], const Unit& u, int wr, int wc, int fr, int fq) const {
;     ...
;             for (int m = 0; m < 4; ++m) { bf16_t* rowp = O + (size_t)(row0 + ai * HALF + m * 16) * ldc + col0;
; #pragma unroll
;                 for (int bj = 0; bj < 2; ++bj) { f32x4 v0 = acc[ai][bj][m][0], v1 = acc[ai][bj][m][1];
;                     if (MODE == 1) {
;                         unsigned g0 = 0u, g1 = 0u;
; #pragma unroll
;                         for (int e = 0; e < 4; ++e) { g0 = __builtin_amdgcn_cvt_pk_u8_f32(fmaxf(floorf(255.f * __builtin_amdgcn_rcpf(1.0f + __builtin_amdgcn_exp2f(v0[e])) + 0.5f), 1.f), e, g0);
;                                                       g1 = __builtin_amdgcn_cvt_pk_u8_f32(fmaxf(floorf(255.f * __builtin_amdgcn_rcpf(1.0f + __builtin_amdgcn_exp2f(v1[e])) + 0.5f), 1.f), e, g1); }
;                         *(u32x2*)((unsigned char*)O + ((size_t)(row0 + ai * HALF + m * 16) * ldc + colt) * 2 + bj * HALF + wc * 32 + 8 * fq) = (u32x2){g0, g1};
;                     } else {
;                     if (u.pn * BM + bj * HALF + wc * 32 + 8 * fq < ZGA + 16) {
;                     u32x4 w; w.x = cvt_pk_bf16(v0[0], v0[1]); w.y = cvt_pk_bf16(v0[2], v0[3]); w.z = cvt_pk_bf16(v1[0], v1[1]); w.w = cvt_pk_bf16(v1[2], v1[3]);
;                     *(u32x4*)(rowp + bj * HALF) = w; } } } }
.LBB0_391:
	v_mov_b32_e32 v0, v246
	s_mov_b32 s11, s12
	s_mov_b32 s40, s52
	s_lshl_b32 s10, s57, 8
	s_lshl_b32 s11, s11, 6
	v_and_b32_e32 v172, 15, v0
	s_add_i32 s41, s11, s10
	v_bfe_u32 v173, v0, 4, 2
	v_or_b32_e32 v130, s41, v172
	v_lshlrev_b32_e32 v0, 15, v173
	v_ashrrev_i32_e32 v131, 31, v130
	s_cmp_eq_u32 s57, s100
	s_cselect_b64 s[98:99], -1, 0
	s_mov_b32 s100, s57
	s_cbranch_scc1 .Lrc0_skip
	v_lshl_add_u64 v[132:133], v[130:131], 0, v[0:1]
	v_lshl_add_u64 v[132:133], v[132:133], 4, s[70:71]
	global_load_dwordx4 v[158:161], v[132:133], off
	v_or_b32_e32 v132, 16, v130
	v_ashrrev_i32_e32 v133, 31, v132
	v_lshl_add_u64 v[132:133], v[132:133], 0, v[0:1]
	v_lshl_add_u64 v[132:133], v[132:133], 4, s[70:71]
	global_load_dwordx4 v[162:165], v[132:133], off
	v_or_b32_e32 v132, 32, v130
	v_ashrrev_i32_e32 v133, 31, v132
	v_lshl_add_u64 v[132:133], v[132:133], 0, v[0:1]
	v_lshl_add_u64 v[132:133], v[132:133], 4, s[70:71]
	global_load_dwordx4 v[176:179], v[132:133], off
	v_or_b32_e32 v132, 48, v130
	v_ashrrev_i32_e32 v133, 31, v132
	v_lshl_add_u64 v[132:133], v[132:133], 0, v[0:1]
	v_lshl_add_u64 v[132:133], v[132:133], 4, s[70:71]
	global_load_dwordx4 v[180:183], v[132:133], off
	v_add_u32_e32 v132, 0x80, v130
	v_ashrrev_i32_e32 v133, 31, v132
	v_lshl_add_u64 v[132:133], v[132:133], 0, v[0:1]
	v_lshl_add_u64 v[132:133], v[132:133], 4, s[70:71]
	global_load_dwordx4 v[184:187], v[132:133], off
	v_add_u32_e32 v132, 0x90, v130
	v_ashrrev_i32_e32 v133, 31, v132
	v_lshl_add_u64 v[132:133], v[132:133], 0, v[0:1]
	v_lshl_add_u64 v[132:133], v[132:133], 4, s[70:71]
	global_load_dwordx4 v[138:141], v[132:133], off
	v_add_u32_e32 v132, 0xa0, v130
	v_ashrrev_i32_e32 v133, 31, v132
	v_lshl_add_u64 v[132:133], v[132:133], 0, v[0:1]
	v_lshl_add_u64 v[132:133], v[132:133], 4, s[70:71]
	global_load_dwordx4 v[134:137], v[132:133], off
	v_add_u32_e32 v130, 0xb0, v130
	v_ashrrev_i32_e32 v131, 31, v130
	v_lshl_add_u64 v[130:131], v[130:131], 0, v[0:1]
	v_lshl_add_u64 v[130:131], v[130:131], 4, s[70:71]
	global_load_dwordx4 v[130:133], v[130:131], off
.Lrc0_skip:
	v_and_b32_e32 v154, 64, v249
	v_xor_b32_e32 v0, 16, v249
	v_add_u32_e32 v154, 64, v154
	v_cmp_lt_i32_e32 vcc, v0, v154
	v_xor_b32_e32 v155, 32, v249
	s_lshl_b32 s41, s56, 8
	v_cndmask_b32_e32 v0, v249, v0, vcc
	v_cmp_lt_i32_e32 vcc, v155, v154
	v_lshlrev_b32_e32 v0, 2, v0
	s_lshl_b32 s40, s40, 5
	v_cndmask_b32_e32 v154, v249, v155, vcc
	v_lshlrev_b32_e32 v188, 2, v154
	s_add_i32 s43, s40, s41
	s_waitcnt vmcnt(0)
	v_mov_b32_e32 v154, v159
	v_mov_b32_e32 v155, v160
	v_mov_b32_e32 v159, v161
	v_pk_add_f32 v[154:155], v[154:155], v[158:159]
	v_mov_b32_e32 v158, v163
	v_mov_b32_e32 v159, v164
	v_mov_b32_e32 v163, v165
	v_pk_add_f32 v[158:159], v[158:159], v[162:163]
	v_add_f32_e32 v154, v154, v155
	v_add_f32_e32 v158, v158, v159
	ds_bpermute_b32 v159, v0, v158
	ds_bpermute_b32 v155, v0, v154
	s_waitcnt lgkmcnt(1)
	v_add_f32_e32 v164, v158, v159
	v_mov_b32_e32 v158, v177
	v_mov_b32_e32 v159, v178
	v_mov_b32_e32 v177, v179
	v_pk_add_f32 v[158:159], v[158:159], v[176:177]
	s_waitcnt lgkmcnt(0)
	v_add_f32_e32 v154, v154, v155
	v_add_f32_e32 v158, v158, v159
	ds_bpermute_b32 v159, v0, v158
	ds_bpermute_b32 v155, v188, v154
	v_mov_b32_e32 v166, v139
	v_mov_b32_e32 v167, v140
	v_mov_b32_e32 v139, v141
	s_waitcnt lgkmcnt(1)
	v_add_f32_e32 v162, v158, v159
	v_mov_b32_e32 v158, v181
	v_mov_b32_e32 v159, v182
	v_mov_b32_e32 v181, v183
	v_mov_b32_e32 v140, v135
	v_mov_b32_e32 v141, v136
	v_mov_b32_e32 v135, v137
	v_pk_add_f32 v[158:159], v[158:159], v[180:181]
	v_pk_add_f32 v[134:135], v[140:141], v[134:135]
	v_add_f32_e32 v158, v158, v159
	v_add_f32_e32 v134, v134, v135
	ds_bpermute_b32 v159, v0, v158
	ds_bpermute_b32 v135, v0, v134
	v_pk_add_f32 v[138:139], v[166:167], v[138:139]
	s_waitcnt lgkmcnt(2)
	v_add_f32_e32 v154, v154, v155
	v_add_f32_e32 v138, v138, v139
	s_waitcnt lgkmcnt(1)
	v_add_f32_e32 v160, v158, v159
	v_mov_b32_e32 v158, v185
	v_mov_b32_e32 v159, v186
	v_mov_b32_e32 v185, v187
	s_waitcnt lgkmcnt(0)
	v_add_f32_e32 v136, v134, v135
	v_mov_b32_e32 v134, v131
	v_mov_b32_e32 v135, v132
	v_mov_b32_e32 v131, v133
	v_pk_add_f32 v[158:159], v[158:159], v[184:185]
	v_pk_add_f32 v[130:131], v[134:135], v[130:131]
	v_add_f32_e32 v158, v158, v159
	v_add_f32_e32 v130, v130, v131
	ds_bpermute_b32 v159, v0, v158
	ds_bpermute_b32 v139, v0, v138
	ds_bpermute_b32 v0, v0, v130
	v_fmamk_f32 v154, v154, 0x3a800000, v247
	v_rsq_f32_e32 v154, v154
	s_nop 0
	v_cndmask_b32_e64 v154, v154, v226, s[98:99]
	v_mov_b32_e32 v226, v154
	s_waitcnt lgkmcnt(2)
	v_add_f32_e32 v158, v158, v159
	s_waitcnt lgkmcnt(1)
	v_add_f32_e32 v138, v138, v139
	s_waitcnt lgkmcnt(0)
	v_add_f32_e32 v0, v130, v0
	ds_bpermute_b32 v165, v188, v164
	ds_bpermute_b32 v163, v188, v162
	ds_bpermute_b32 v161, v188, v160
	ds_bpermute_b32 v159, v188, v158
	ds_bpermute_b32 v139, v188, v138
	ds_bpermute_b32 v137, v188, v136
	ds_bpermute_b32 v134, v188, v0
	v_lshlrev_b32_e32 v132, 3, v173
	v_or_b32_e32 v131, s11, v172
	v_or_b32_e32 v130, s43, v132
	v_add_u32_e32 v135, s10, v131
	v_or_b32_e32 v140, s40, v132
	v_mov_b64_e32 v[132:133], s[68:69]
	v_mad_i64_i32 v[132:133], s[10:11], v135, s74, v[132:133]
	v_ashrrev_i32_e32 v131, 31, v130
	v_add_u32_e32 v140, s41, v140
	s_movk_i32 s10, 0x1110
	v_mov_b32_e32 v155, v154
	v_lshl_add_u64 v[132:133], v[130:131], 1, v[132:133]
	v_cmp_gt_i32_e32 vcc, s10, v140
	s_and_saveexec_b64 s[10:11], vcc
	s_cbranch_execz .LBB0_393
	v_mov_b32_e32 v166, v154
	v_mov_b32_e32 v167, v154
	v_pk_mul_f32 v[176:177], v[124:125], v[166:167]
	v_pk_mul_f32 v[124:125], v[122:123], v[154:155]
	v_pk_mul_f32 v[122:123], v[126:127], v[154:155]
	v_pk_mul_f32 v[128:129], v[128:129], v[166:167]
	s_nop 1
	v_cvt_pk_bf16_f32 v122, v122, v123
	s_nop 0
	s_nop 1
	v_cvt_pk_bf16_f32 v123, v128, v129
	s_nop 1
	v_cvt_pk_bf16_f32 v124, v124, v125
	s_nop 1
	v_cvt_pk_bf16_f32 v125, v176, v177
	global_store_dwordx4 v[132:133], v[122:125], off

; __device__ __forceinline__ unsigned cvt_pk_bf16(float lo, float hi) { unsigned r; asm volatile("s_nop 1\n\tv_cvt_pk_bf16_f32 %0, %1, %2" : "=v"(r) : "v"(lo), "v"(hi)); return r; }
;     ...
;         for (int m = 0; m < 4; ++m) { float sq = (p[ai][m].x + p[ai][m].y) + (p[ai][m].z + p[ai][m].w);
;             sq += __shfl_xor(sq, 16); sq += __shfl_xor(sq, 32);
;             const float rs = __builtin_amdgcn_rsqf(sq * (1.0f / DM) + EPS) * mul;
; #pragma unroll
;             for (int bj = 0; bj < 2; ++bj)
; #pragma unroll
;                 for (int n = 0; n < 2; ++n) acc[ai][bj][m][n] = acc[ai][bj][m][n] * rs; }
;     __device__ __forceinline__ void operator()(f32x4 (&acc)[2][2][4][2], const Unit& u, int wr, int wc, int fr, int fq) const {
;     ...
;             for (int m = 0; m < 4; ++m) { bf16_t* rowp = O + (size_t)(row0 + ai * HALF + m * 16) * ldc + col0;
; #pragma unroll
;                 for (int bj = 0; bj < 2; ++bj) { f32x4 v0 = acc[ai][bj][m][0], v1 = acc[ai][bj][m][1];
;                     if (MODE == 1) {
;                         unsigned g0 = 0u, g1 = 0u;
; #pragma unroll
;                         for (int e = 0; e < 4; ++e) { g0 = __builtin_amdgcn_cvt_pk_u8_f32(fmaxf(floorf(255.f * __builtin_amdgcn_rcpf(1.0f + __builtin_amdgcn_exp2f(v0[e])) + 0.5f), 1.f), e, g0);
;                                                       g1 = __builtin_amdgcn_cvt_pk_u8_f32(fmaxf(floorf(255.f * __builtin_amdgcn_rcpf(1.0f + __builtin_amdgcn_exp2f(v1[e])) + 0.5f), 1.f), e, g1); }
;                         *(u32x2*)((unsigned char*)O + ((size_t)(row0 + ai * HALF + m * 16) * ldc + colt) * 2 + bj * HALF + wc * 32 + 8 * fq) = (u32x2){g0, g1};
;                     } else {
;                     if (u.pn * BM + bj * HALF + wc * 32 + 8 * fq < ZGA + 16) {
;                     u32x4 w; w.x = cvt_pk_bf16(v0[0], v0[1]); w.y = cvt_pk_bf16(v0[2], v0[3]); w.z = cvt_pk_bf16(v1[0], v1[1]); w.w = cvt_pk_bf16(v1[2], v1[3]);
;                     *(u32x4*)(rowp + bj * HALF) = w; } } } }
.LBB0_395:
	s_or_b64 exec, exec, s[10:11]
	s_waitcnt lgkmcnt(6)
	v_add_f32_e32 v114, v164, v165
	v_fmamk_f32 v114, v114, 0x3a800000, v247
	v_rsq_f32_e32 v116, v114
	s_nop 0
	v_cndmask_b32_e64 v116, v116, v227, s[98:99]
	v_mov_b32_e32 v227, v116
	v_or_b32_e32 v118, 16, v135
	v_mov_b64_e32 v[114:115], s[68:69]
	v_mad_i64_i32 v[114:115], s[10:11], v118, s74, v[114:115]
	v_mov_b32_e32 v117, v116
	v_lshl_add_u64 v[114:115], v[130:131], 1, v[114:115]
	s_and_saveexec_b64 s[10:11], vcc
	s_mov_b32 s94, s96
	s_cbranch_execz .LBB0_397
	v_mov_b32_e32 v118, v116
	v_mov_b32_e32 v119, v116
	v_pk_mul_f32 v[112:113], v[112:113], v[118:119]
	v_pk_mul_f32 v[118:119], v[108:109], v[118:119]
	v_pk_mul_f32 v[108:109], v[106:107], v[116:117]
	v_pk_mul_f32 v[110:111], v[110:111], v[116:117]
	s_nop 0
	s_nop 1
	v_cvt_pk_bf16_f32 v106, v110, v111
	s_nop 1
	v_cvt_pk_bf16_f32 v107, v112, v113
	s_nop 1
	v_cvt_pk_bf16_f32 v108, v108, v109
	s_nop 1
	v_cvt_pk_bf16_f32 v109, v118, v119
	global_store_dwordx4 v[114:115], v[106:109], off

; __device__ __forceinline__ unsigned cvt_pk_bf16(float lo, float hi) { unsigned r; asm volatile("s_nop 1\n\tv_cvt_pk_bf16_f32 %0, %1, %2" : "=v"(r) : "v"(lo), "v"(hi)); return r; }
;     ...
;         for (int m = 0; m < 4; ++m) { float sq = (p[ai][m].x + p[ai][m].y) + (p[ai][m].z + p[ai][m].w);
;             sq += __shfl_xor(sq, 16); sq += __shfl_xor(sq, 32);
;             const float rs = __builtin_amdgcn_rsqf(sq * (1.0f / DM) + EPS) * mul;
; #pragma unroll
;             for (int bj = 0; bj < 2; ++bj)
; #pragma unroll
;                 for (int n = 0; n < 2; ++n) acc[ai][bj][m][n] = acc[ai][bj][m][n] * rs; }
;     __device__ __forceinline__ void operator()(f32x4 (&acc)[2][2][4][2], const Unit& u, int wr, int wc, int fr, int fq) const {
;     ...
;             for (int m = 0; m < 4; ++m) { bf16_t* rowp = O + (size_t)(row0 + ai * HALF + m * 16) * ldc + col0;
; #pragma unroll
;                 for (int bj = 0; bj < 2; ++bj) { f32x4 v0 = acc[ai][bj][m][0], v1 = acc[ai][bj][m][1];
;                     if (MODE == 1) {
;                         unsigned g0 = 0u, g1 = 0u;
; #pragma unroll
;                         for (int e = 0; e < 4; ++e) { g0 = __builtin_amdgcn_cvt_pk_u8_f32(fmaxf(floorf(255.f * __builtin_amdgcn_rcpf(1.0f + __builtin_amdgcn_exp2f(v0[e])) + 0.5f), 1.f), e, g0);
;                                                       g1 = __builtin_amdgcn_cvt_pk_u8_f32(fmaxf(floorf(255.f * __builtin_amdgcn_rcpf(1.0f + __builtin_amdgcn_exp2f(v1[e])) + 0.5f), 1.f), e, g1); }
;                         *(u32x2*)((unsigned char*)O + ((size_t)(row0 + ai * HALF + m * 16) * ldc + colt) * 2 + bj * HALF + wc * 32 + 8 * fq) = (u32x2){g0, g1};
;                     } else {
;                     if (u.pn * BM + bj * HALF + wc * 32 + 8 * fq < ZGA + 16) {
;                     u32x4 w; w.x = cvt_pk_bf16(v0[0], v0[1]); w.y = cvt_pk_bf16(v0[2], v0[3]); w.z = cvt_pk_bf16(v1[0], v1[1]); w.w = cvt_pk_bf16(v1[2], v1[3]);
;                     *(u32x4*)(rowp + bj * HALF) = w; } } } }
.LBB0_399:
	s_or_b64 exec, exec, s[10:11]
	s_waitcnt lgkmcnt(5)
	v_add_f32_e32 v98, v162, v163
	v_fmamk_f32 v98, v98, 0x3a800000, v247
	v_rsq_f32_e32 v100, v98
	s_nop 0
	v_cndmask_b32_e64 v100, v100, v228, s[98:99]
	v_mov_b32_e32 v228, v100
	v_or_b32_e32 v102, 32, v135
	v_mov_b64_e32 v[98:99], s[68:69]
	v_mad_i64_i32 v[98:99], s[10:11], v102, s74, v[98:99]
	v_mov_b32_e32 v101, v100
	v_lshl_add_u64 v[98:99], v[130:131], 1, v[98:99]
	s_and_saveexec_b64 s[10:11], vcc
	s_cbranch_execz .LBB0_401
	v_mov_b32_e32 v102, v100
	v_mov_b32_e32 v103, v100
	v_pk_mul_f32 v[96:97], v[96:97], v[102:103]
	v_pk_mul_f32 v[102:103], v[92:93], v[102:103]
	v_pk_mul_f32 v[92:93], v[90:91], v[100:101]
	v_pk_mul_f32 v[94:95], v[94:95], v[100:101]
	s_nop 0
	s_nop 1
	v_cvt_pk_bf16_f32 v90, v94, v95
	s_nop 1
	v_cvt_pk_bf16_f32 v91, v96, v97
	s_nop 1
	v_cvt_pk_bf16_f32 v92, v92, v93
	s_nop 1
	v_cvt_pk_bf16_f32 v93, v102, v103
	global_store_dwordx4 v[98:99], v[90:93], off

; __device__ __forceinline__ unsigned cvt_pk_bf16(float lo, float hi) { unsigned r; asm volatile("s_nop 1\n\tv_cvt_pk_bf16_f32 %0, %1, %2" : "=v"(r) : "v"(lo), "v"(hi)); return r; }
;     ...
;         for (int m = 0; m < 4; ++m) { float sq = (p[ai][m].x + p[ai][m].y) + (p[ai][m].z + p[ai][m].w);
;             sq += __shfl_xor(sq, 16); sq += __shfl_xor(sq, 32);
;             const float rs = __builtin_amdgcn_rsqf(sq * (1.0f / DM) + EPS) * mul;
; #pragma unroll
;             for (int bj = 0; bj < 2; ++bj)
; #pragma unroll
;                 for (int n = 0; n < 2; ++n) acc[ai][bj][m][n] = acc[ai][bj][m][n] * rs; }
;     __device__ __forceinline__ void operator()(f32x4 (&acc)[2][2][4][2], const Unit& u, int wr, int wc, int fr, int fq) const {
;     ...
;             for (int m = 0; m < 4; ++m) { bf16_t* rowp = O + (size_t)(row0 + ai * HALF + m * 16) * ldc + col0;
; #pragma unroll
;                 for (int bj = 0; bj < 2; ++bj) { f32x4 v0 = acc[ai][bj][m][0], v1 = acc[ai][bj][m][1];
;                     if (MODE == 1) {
;                         unsigned g0 = 0u, g1 = 0u;
; #pragma unroll
;                         for (int e = 0; e < 4; ++e) { g0 = __builtin_amdgcn_cvt_pk_u8_f32(fmaxf(floorf(255.f * __builtin_amdgcn_rcpf(1.0f + __builtin_amdgcn_exp2f(v0[e])) + 0.5f), 1.f), e, g0);
;                                                       g1 = __builtin_amdgcn_cvt_pk_u8_f32(fmaxf(floorf(255.f * __builtin_amdgcn_rcpf(1.0f + __builtin_amdgcn_exp2f(v1[e])) + 0.5f), 1.f), e, g1); }
;                         *(u32x2*)((unsigned char*)O + ((size_t)(row0 + ai * HALF + m * 16) * ldc + colt) * 2 + bj * HALF + wc * 32 + 8 * fq) = (u32x2){g0, g1};
;                     } else {
;                     if (u.pn * BM + bj * HALF + wc * 32 + 8 * fq < ZGA + 16) {
;                     u32x4 w; w.x = cvt_pk_bf16(v0[0], v0[1]); w.y = cvt_pk_bf16(v0[2], v0[3]); w.z = cvt_pk_bf16(v1[0], v1[1]); w.w = cvt_pk_bf16(v1[2], v1[3]);
;                     *(u32x4*)(rowp + bj * HALF) = w; } } } }
.LBB0_403:
	s_or_b64 exec, exec, s[10:11]
	s_waitcnt lgkmcnt(4)
	v_add_f32_e32 v82, v160, v161
	v_fmamk_f32 v82, v82, 0x3a800000, v247
	v_rsq_f32_e32 v84, v82
	s_nop 0
	v_cndmask_b32_e64 v84, v84, v229, s[98:99]
	v_mov_b32_e32 v229, v84
	v_or_b32_e32 v86, 48, v135
	v_mov_b64_e32 v[82:83], s[68:69]
	v_mad_i64_i32 v[82:83], s[10:11], v86, s74, v[82:83]
	v_mov_b32_e32 v85, v84
	v_lshl_add_u64 v[82:83], v[130:131], 1, v[82:83]
	s_and_saveexec_b64 s[10:11], vcc
	s_cbranch_execz .LBB0_405
	v_mov_b32_e32 v86, v84
	v_mov_b32_e32 v87, v84
	v_pk_mul_f32 v[80:81], v[80:81], v[86:87]
	v_pk_mul_f32 v[86:87], v[76:77], v[86:87]
	v_pk_mul_f32 v[76:77], v[74:75], v[84:85]
	v_pk_mul_f32 v[78:79], v[78:79], v[84:85]
	s_nop 0
	s_nop 1
	v_cvt_pk_bf16_f32 v74, v78, v79
	s_nop 1
	v_cvt_pk_bf16_f32 v75, v80, v81
	s_nop 1
	v_cvt_pk_bf16_f32 v76, v76, v77
	s_nop 1
	v_cvt_pk_bf16_f32 v77, v86, v87
	global_store_dwordx4 v[82:83], v[74:77], off

; __device__ __forceinline__ unsigned cvt_pk_bf16(float lo, float hi) { unsigned r; asm volatile("s_nop 1\n\tv_cvt_pk_bf16_f32 %0, %1, %2" : "=v"(r) : "v"(lo), "v"(hi)); return r; }
;     ...
;         for (int m = 0; m < 4; ++m) { float sq = (p[ai][m].x + p[ai][m].y) + (p[ai][m].z + p[ai][m].w);
;             sq += __shfl_xor(sq, 16); sq += __shfl_xor(sq, 32);
;             const float rs = __builtin_amdgcn_rsqf(sq * (1.0f / DM) + EPS) * mul;
; #pragma unroll
;             for (int bj = 0; bj < 2; ++bj)
; #pragma unroll
;                 for (int n = 0; n < 2; ++n) acc[ai][bj][m][n] = acc[ai][bj][m][n] * rs; }
;     __device__ __forceinline__ void operator()(f32x4 (&acc)[2][2][4][2], const Unit& u, int wr, int wc, int fr, int fq) const {
;     ...
;             for (int m = 0; m < 4; ++m) { bf16_t* rowp = O + (size_t)(row0 + ai * HALF + m * 16) * ldc + col0;
; #pragma unroll
;                 for (int bj = 0; bj < 2; ++bj) { f32x4 v0 = acc[ai][bj][m][0], v1 = acc[ai][bj][m][1];
;                     if (MODE == 1) {
;                         unsigned g0 = 0u, g1 = 0u;
; #pragma unroll
;                         for (int e = 0; e < 4; ++e) { g0 = __builtin_amdgcn_cvt_pk_u8_f32(fmaxf(floorf(255.f * __builtin_amdgcn_rcpf(1.0f + __builtin_amdgcn_exp2f(v0[e])) + 0.5f), 1.f), e, g0);
;                                                       g1 = __builtin_amdgcn_cvt_pk_u8_f32(fmaxf(floorf(255.f * __builtin_amdgcn_rcpf(1.0f + __builtin_amdgcn_exp2f(v1[e])) + 0.5f), 1.f), e, g1); }
;                         *(u32x2*)((unsigned char*)O + ((size_t)(row0 + ai * HALF + m * 16) * ldc + colt) * 2 + bj * HALF + wc * 32 + 8 * fq) = (u32x2){g0, g1};
;                     } else {
;                     if (u.pn * BM + bj * HALF + wc * 32 + 8 * fq < ZGA + 16) {
;                     u32x4 w; w.x = cvt_pk_bf16(v0[0], v0[1]); w.y = cvt_pk_bf16(v0[2], v0[3]); w.z = cvt_pk_bf16(v1[0], v1[1]); w.w = cvt_pk_bf16(v1[2], v1[3]);
;                     *(u32x4*)(rowp + bj * HALF) = w; } } } }
.LBB0_407:
	s_or_b64 exec, exec, s[10:11]
	s_waitcnt lgkmcnt(3)
	v_add_f32_e32 v66, v158, v159
	v_fmamk_f32 v66, v66, 0x3a800000, v247
	v_rsq_f32_e32 v68, v66
	s_nop 0
	v_cndmask_b32_e64 v68, v68, v230, s[98:99]
	v_mov_b32_e32 v230, v68
	v_add_u32_e32 v70, 0x80, v135
	v_mov_b64_e32 v[66:67], s[68:69]
	v_mad_i64_i32 v[66:67], s[10:11], v70, s74, v[66:67]
	v_mov_b32_e32 v69, v68
	v_lshl_add_u64 v[66:67], v[130:131], 1, v[66:67]
	s_and_saveexec_b64 s[10:11], vcc
	s_cbranch_execz .LBB0_409
	v_mov_b32_e32 v70, v68
	v_mov_b32_e32 v71, v68
	v_pk_mul_f32 v[64:65], v[64:65], v[70:71]
	v_pk_mul_f32 v[70:71], v[60:61], v[70:71]
	v_pk_mul_f32 v[60:61], v[58:59], v[68:69]
	v_pk_mul_f32 v[62:63], v[62:63], v[68:69]
	s_nop 0
	s_nop 1
	v_cvt_pk_bf16_f32 v58, v62, v63
	s_nop 1
	v_cvt_pk_bf16_f32 v59, v64, v65
	s_nop 1
	v_cvt_pk_bf16_f32 v60, v60, v61
	s_nop 1
	v_cvt_pk_bf16_f32 v61, v70, v71
	global_store_dwordx4 v[66:67], v[58:61], off

; __device__ __forceinline__ unsigned cvt_pk_bf16(float lo, float hi) { unsigned r; asm volatile("s_nop 1\n\tv_cvt_pk_bf16_f32 %0, %1, %2" : "=v"(r) : "v"(lo), "v"(hi)); return r; }
;     ...
;         for (int m = 0; m < 4; ++m) { float sq = (p[ai][m].x + p[ai][m].y) + (p[ai][m].z + p[ai][m].w);
;             sq += __shfl_xor(sq, 16); sq += __shfl_xor(sq, 32);
;             const float rs = __builtin_amdgcn_rsqf(sq * (1.0f / DM) + EPS) * mul;
; #pragma unroll
;             for (int bj = 0; bj < 2; ++bj)
; #pragma unroll
;                 for (int n = 0; n < 2; ++n) acc[ai][bj][m][n] = acc[ai][bj][m][n] * rs; }
;     __device__ __forceinline__ void operator()(f32x4 (&acc)[2][2][4][2], const Unit& u, int wr, int wc, int fr, int fq) const {
;     ...
;             for (int m = 0; m < 4; ++m) { bf16_t* rowp = O + (size_t)(row0 + ai * HALF + m * 16) * ldc + col0;
; #pragma unroll
;                 for (int bj = 0; bj < 2; ++bj) { f32x4 v0 = acc[ai][bj][m][0], v1 = acc[ai][bj][m][1];
;                     if (MODE == 1) {
;                         unsigned g0 = 0u, g1 = 0u;
; #pragma unroll
;                         for (int e = 0; e < 4; ++e) { g0 = __builtin_amdgcn_cvt_pk_u8_f32(fmaxf(floorf(255.f * __builtin_amdgcn_rcpf(1.0f + __builtin_amdgcn_exp2f(v0[e])) + 0.5f), 1.f), e, g0);
;                                                       g1 = __builtin_amdgcn_cvt_pk_u8_f32(fmaxf(floorf(255.f * __builtin_amdgcn_rcpf(1.0f + __builtin_amdgcn_exp2f(v1[e])) + 0.5f), 1.f), e, g1); }
;                         *(u32x2*)((unsigned char*)O + ((size_t)(row0 + ai * HALF + m * 16) * ldc + colt) * 2 + bj * HALF + wc * 32 + 8 * fq) = (u32x2){g0, g1};
;                     } else {
;                     if (u.pn * BM + bj * HALF + wc * 32 + 8 * fq < ZGA + 16) {
;                     u32x4 w; w.x = cvt_pk_bf16(v0[0], v0[1]); w.y = cvt_pk_bf16(v0[2], v0[3]); w.z = cvt_pk_bf16(v1[0], v1[1]); w.w = cvt_pk_bf16(v1[2], v1[3]);
;                     *(u32x4*)(rowp + bj * HALF) = w; } } } }
.LBB0_411:
	s_or_b64 exec, exec, s[10:11]
	s_waitcnt lgkmcnt(2)
	v_add_f32_e32 v50, v138, v139
	v_fmamk_f32 v50, v50, 0x3a800000, v247
	v_rsq_f32_e32 v52, v50
	s_nop 0
	v_cndmask_b32_e64 v52, v52, v231, s[98:99]
	v_mov_b32_e32 v231, v52
	v_add_u32_e32 v54, 0x90, v135
	v_mov_b64_e32 v[50:51], s[68:69]
	v_mad_i64_i32 v[50:51], s[10:11], v54, s74, v[50:51]
	v_mov_b32_e32 v53, v52
	v_lshl_add_u64 v[50:51], v[130:131], 1, v[50:51]
	s_and_saveexec_b64 s[10:11], vcc
	s_cbranch_execz .LBB0_413
	v_mov_b32_e32 v54, v52
	v_mov_b32_e32 v55, v52
	v_pk_mul_f32 v[48:49], v[48:49], v[54:55]
	v_pk_mul_f32 v[54:55], v[44:45], v[54:55]
	v_pk_mul_f32 v[44:45], v[42:43], v[52:53]
	v_pk_mul_f32 v[46:47], v[46:47], v[52:53]
	s_nop 0
	s_nop 1
	v_cvt_pk_bf16_f32 v42, v46, v47
	s_nop 1
	v_cvt_pk_bf16_f32 v43, v48, v49
	s_nop 1
	v_cvt_pk_bf16_f32 v44, v44, v45
	s_nop 1
	v_cvt_pk_bf16_f32 v45, v54, v55
	global_store_dwordx4 v[50:51], v[42:45], off

; __device__ __forceinline__ unsigned cvt_pk_bf16(float lo, float hi) { unsigned r; asm volatile("s_nop 1\n\tv_cvt_pk_bf16_f32 %0, %1, %2" : "=v"(r) : "v"(lo), "v"(hi)); return r; }
;     ...
;         for (int m = 0; m < 4; ++m) { float sq = (p[ai][m].x + p[ai][m].y) + (p[ai][m].z + p[ai][m].w);
;             sq += __shfl_xor(sq, 16); sq += __shfl_xor(sq, 32);
;             const float rs = __builtin_amdgcn_rsqf(sq * (1.0f / DM) + EPS) * mul;
; #pragma unroll
;             for (int bj = 0; bj < 2; ++bj)
; #pragma unroll
;                 for (int n = 0; n < 2; ++n) acc[ai][bj][m][n] = acc[ai][bj][m][n] * rs; }
;     __device__ __forceinline__ void operator()(f32x4 (&acc)[2][2][4][2], const Unit& u, int wr, int wc, int fr, int fq) const {
;     ...
;             for (int m = 0; m < 4; ++m) { bf16_t* rowp = O + (size_t)(row0 + ai * HALF + m * 16) * ldc + col0;
; #pragma unroll
;                 for (int bj = 0; bj < 2; ++bj) { f32x4 v0 = acc[ai][bj][m][0], v1 = acc[ai][bj][m][1];
;                     if (MODE == 1) {
;                         unsigned g0 = 0u, g1 = 0u;
; #pragma unroll
;                         for (int e = 0; e < 4; ++e) { g0 = __builtin_amdgcn_cvt_pk_u8_f32(fmaxf(floorf(255.f * __builtin_amdgcn_rcpf(1.0f + __builtin_amdgcn_exp2f(v0[e])) + 0.5f), 1.f), e, g0);
;                                                       g1 = __builtin_amdgcn_cvt_pk_u8_f32(fmaxf(floorf(255.f * __builtin_amdgcn_rcpf(1.0f + __builtin_amdgcn_exp2f(v1[e])) + 0.5f), 1.f), e, g1); }
;                         *(u32x2*)((unsigned char*)O + ((size_t)(row0 + ai * HALF + m * 16) * ldc + colt) * 2 + bj * HALF + wc * 32 + 8 * fq) = (u32x2){g0, g1};
;                     } else {
;                     if (u.pn * BM + bj * HALF + wc * 32 + 8 * fq < ZGA + 16) {
;                     u32x4 w; w.x = cvt_pk_bf16(v0[0], v0[1]); w.y = cvt_pk_bf16(v0[2], v0[3]); w.z = cvt_pk_bf16(v1[0], v1[1]); w.w = cvt_pk_bf16(v1[2], v1[3]);
;                     *(u32x4*)(rowp + bj * HALF) = w; } } } }
.LBB0_415:
	s_or_b64 exec, exec, s[10:11]
	s_waitcnt lgkmcnt(1)
	v_add_f32_e32 v34, v136, v137
	v_fmamk_f32 v34, v34, 0x3a800000, v247
	v_rsq_f32_e32 v36, v34
	s_nop 0
	v_cndmask_b32_e64 v36, v36, v232, s[98:99]
	v_mov_b32_e32 v232, v36
	v_add_u32_e32 v38, 0xa0, v135
	v_mov_b64_e32 v[34:35], s[68:69]
	v_mad_i64_i32 v[34:35], s[10:11], v38, s74, v[34:35]
	v_mov_b32_e32 v37, v36
	v_lshl_add_u64 v[34:35], v[130:131], 1, v[34:35]
	s_and_saveexec_b64 s[10:11], vcc
	s_cbranch_execz .LBB0_417
	v_mov_b32_e32 v38, v36
	v_mov_b32_e32 v39, v36
	v_pk_mul_f32 v[32:33], v[32:33], v[38:39]
	v_pk_mul_f32 v[38:39], v[28:29], v[38:39]
	v_pk_mul_f32 v[28:29], v[26:27], v[36:37]
	v_pk_mul_f32 v[30:31], v[30:31], v[36:37]
	s_nop 0
	s_nop 1
	v_cvt_pk_bf16_f32 v26, v30, v31
	s_nop 1
	v_cvt_pk_bf16_f32 v27, v32, v33
	s_nop 1
	v_cvt_pk_bf16_f32 v28, v28, v29
	s_nop 1
	v_cvt_pk_bf16_f32 v29, v38, v39
	global_store_dwordx4 v[34:35], v[26:29], off

; __device__ __forceinline__ unsigned cvt_pk_bf16(float lo, float hi) { unsigned r; asm volatile("s_nop 1\n\tv_cvt_pk_bf16_f32 %0, %1, %2" : "=v"(r) : "v"(lo), "v"(hi)); return r; }
;     ...
;         for (int m = 0; m < 4; ++m) { float sq = (p[ai][m].x + p[ai][m].y) + (p[ai][m].z + p[ai][m].w);
;             sq += __shfl_xor(sq, 16); sq += __shfl_xor(sq, 32);
;             const float rs = __builtin_amdgcn_rsqf(sq * (1.0f / DM) + EPS) * mul;
; #pragma unroll
;             for (int bj = 0; bj < 2; ++bj)
; #pragma unroll
;                 for (int n = 0; n < 2; ++n) acc[ai][bj][m][n] = acc[ai][bj][m][n] * rs; }
;     __device__ __forceinline__ void operator()(f32x4 (&acc)[2][2][4][2], const Unit& u, int wr, int wc, int fr, int fq) const {
;     ...
;             for (int m = 0; m < 4; ++m) { bf16_t* rowp = O + (size_t)(row0 + ai * HALF + m * 16) * ldc + col0;
; #pragma unroll
;                 for (int bj = 0; bj < 2; ++bj) { f32x4 v0 = acc[ai][bj][m][0], v1 = acc[ai][bj][m][1];
;                     if (MODE == 1) {
;                         unsigned g0 = 0u, g1 = 0u;
; #pragma unroll
;                         for (int e = 0; e < 4; ++e) { g0 = __builtin_amdgcn_cvt_pk_u8_f32(fmaxf(floorf(255.f * __builtin_amdgcn_rcpf(1.0f + __builtin_amdgcn_exp2f(v0[e])) + 0.5f), 1.f), e, g0);
;                                                       g1 = __builtin_amdgcn_cvt_pk_u8_f32(fmaxf(floorf(255.f * __builtin_amdgcn_rcpf(1.0f + __builtin_amdgcn_exp2f(v1[e])) + 0.5f), 1.f), e, g1); }
;                         *(u32x2*)((unsigned char*)O + ((size_t)(row0 + ai * HALF + m * 16) * ldc + colt) * 2 + bj * HALF + wc * 32 + 8 * fq) = (u32x2){g0, g1};
;                     } else {
;                     if (u.pn * BM + bj * HALF + wc * 32 + 8 * fq < ZGA + 16) {
;                     u32x4 w; w.x = cvt_pk_bf16(v0[0], v0[1]); w.y = cvt_pk_bf16(v0[2], v0[3]); w.z = cvt_pk_bf16(v1[0], v1[1]); w.w = cvt_pk_bf16(v1[2], v1[3]);
;                     *(u32x4*)(rowp + bj * HALF) = w; } } } }
.LBB0_419:
	s_or_b64 exec, exec, s[10:11]
	s_waitcnt lgkmcnt(0)
	v_add_f32_e32 v0, v0, v134
	v_fmamk_f32 v0, v0, 0x3a800000, v247
	v_rsq_f32_e32 v20, v0
	s_nop 0
	v_cndmask_b32_e64 v20, v20, v233, s[98:99]
	v_mov_b32_e32 v233, v20
	v_add_u32_e32 v0, 0xb0, v135
	v_mov_b64_e32 v[18:19], s[68:69]
	v_mad_i64_i32 v[18:19], s[10:11], v0, s74, v[18:19]
	v_mov_b32_e32 v21, v20
	v_lshl_add_u64 v[18:19], v[130:131], 1, v[18:19]
	s_and_saveexec_b64 s[10:11], vcc
	s_cbranch_execnz .LBB0_422
	s_or_b64 exec, exec, s[10:11]
	s_and_saveexec_b64 s[10:11], s[40:41]
	s_cbranch_execnz .LBB0_423

; __device__ __forceinline__ int fresh_tid() { int t = threadIdx.x; asm volatile("" : "+v"(t)); return t; }
; #define PG8_STAGE(bufoff, gbase, voff) do { _Pragma("unroll") for (int _i = 0; _i < 2; ++_i) \
;         __builtin_amdgcn_global_load_lds((const unsigned*)((const char*)(gbase) + (voff)[_i]), (LAS unsigned*)(lds + (bufoff) + ldsw + _i * 8192), 16, 0, 0); } while (0)
; #define PG8_WAIT_V(n) asm volatile("s_waitcnt vmcnt(" #n ")" ::: "memory")
; template <class Epi, class Sched, int NSEG, int KK, int LDA, int LDB>
; __device__ __forceinline__ void gemm_phase(LAS unsigned char* lds, const Gemm g, const Sched& S, const Epi& E) {
;     const int tid = fresh_tid(), wid = __builtin_amdgcn_readfirstlane(tid >> 6), lane = tid & 63, wr = wid >> 2, wc = wid & 3, fr = lane & 15, fq = lane >> 4;
;     constexpr int nt = KK / BK;
;     unsigned voffA[2], voffB[2];
; #pragma unroll
;     for (int i = 0; i < 2; ++i) { int R, C; stage_rc(tid * 16 + i * 8192, R, C); const int Rb = Epi::PERM ? ((R & ~31) + perm32(R & 31)) : R;
;         voffA[i] = (unsigned)(R * LDA + C) * 2u; voffB[i] = (unsigned)(Rb * LDB + C) * 2u; }
;     constexpr size_t kstep = (size_t)(BK * 2);
;     constexpr size_t hstepA = (size_t)HALF * LDA * 2, hstepB = (size_t)HALF * LDB * 2;
;     constexpr size_t tstepA = 2 * hstepA, tstepB = 2 * hstepB;
;     const unsigned ldsw = (unsigned)wid * 1024u;
;     const int aoff = lds_byte(wr * 64 + fr, fq * 8), boff = lds_byte(wc * 32 + fr, fq * 8);
;     ...
;     Unit cur, nxt; int ui = 0;
;     if (!S.next(0, cur)) return;
;     f32x4 acc[2][2][4][2];
; #pragma unroll
;     for (int a = 0; a < 2; ++a)
; #pragma unroll
;         for (int b = 0; b < 2; ++b)
; #pragma unroll
;             for (int m = 0; m < 4; ++m)
; #pragma unroll
;                 for (int n = 0; n < 2; ++n) acc[a][b][m][n] = (f32x4){0.f, 0.f, 0.f, 0.f};
;     bf16x8 At[4][2], B0[2][2], B1[2][2];
;     const char* cA = PG8_APTR(cur); const char* cB = PG8_BPTR(cur);
;     PG8_STAGE(PG8_SB(0, 0), cB, voffB); PG8_STAGE(PG8_SB(0, 1), cB + hstepB, voffB); PG8_STAGE(PG8_SA(0, 0), cA, voffA); PG8_STAGE(PG8_SA(0, 1), cA + hstepA, voffA);
;     if (wr == 1) PG8_BAR;
;     PG8_WAIT_V(2); PG8_BAR;
;     PG8_STAGE(PG8_SB(1, 0), cB + kstep, voffB); PG8_STAGE(PG8_SA(1, 0), cA + kstep, voffA); PG8_STAGE(PG8_SB(1, 1), cB + hstepB + kstep, voffB);
;     PG8_WAIT_V(6); PG8_BAR;
.LBB0_668:
	s_or_b64 exec, exec, s[0:1]
	v_readlane_b32 s0, v255, 20
	v_mov_b32_e32 v7, v246
	v_readlane_b32 s1, v255, 21
	s_waitcnt lgkmcnt(0)
	s_barrier
	s_mov_b32 s101, 0
	s_mov_b32 s100, -1
	s_andn2_b64 vcc, exec, s[0:1]
	v_readfirstlane_b32 s8, v7
	s_cbranch_vccnz .LBB0_700
	v_lshlrev_b32_e32 v4, 4, v7
	v_add_u32_e32 v2, 0x2000, v4
	v_ashrrev_i32_e32 v0, 31, v2
	v_lshrrev_b32_e32 v0, 22, v0
	v_add_u32_e32 v0, v2, v0
	v_ashrrev_i32_e32 v0, 10, v0
	v_mul_i32_i24_e32 v3, 0x400, v0
	v_sub_u32_e32 v2, v2, v3
	v_lshrrev_b32_e32 v3, 4, v2
	v_bitop3_b32 v3, v3, v2, 32 bitop3:0x6c
	v_ashrrev_i32_e32 v2, 31, v3
	v_lshrrev_b32_e32 v2, 26, v2
	v_add_u32_e32 v5, v3, v2
	v_lshlrev_b32_e32 v6, 3, v0
	v_readlane_b32 s0, v254, 22
	v_ashrrev_i32_e32 v2, 6, v5
	v_and_b32_e32 v6, -16, v6
	s_add_u32 s12, s0, 0x900000
	v_readlane_b32 s0, v254, 23
	v_add_u32_e32 v6, v2, v6
	s_addc_u32 s13, s0, 0
	v_and_b32_e32 v8, 3, v2
	s_mov_b32 s0, 0x1fffe0
	v_lshrrev_b32_e32 v9, 2, v6
	v_lshlrev_b32_e32 v10, 1, v6
	v_and_b32_e32 v5, 0xc0, v5
	v_and_or_b32 v8, v6, s0, v8
	v_and_b32_e32 v9, 4, v9
	v_and_b32_e32 v10, 24, v10
	v_sub_u32_e32 v3, v3, v5
	v_or3_b32 v8, v8, v9, v10
	v_lshlrev_b32_e32 v9, 5, v0
	v_ashrrev_i16_sdwa v3, v248, sext(v3) dst_sel:DWORD dst_unused:UNUSED_PAD src0_sel:DWORD src1_sel:BYTE_0
	v_and_b32_e32 v9, 32, v9
	v_bfe_i32 v3, v3, 0, 16
	v_add_lshl_u32 v5, v9, v3, 1
	v_lshl_add_u32 v142, v8, 11, v5
	v_lshl_add_u32 v144, v6, 11, v5
	v_bfe_i32 v5, v7, 27, 1
	v_lshrrev_b32_e32 v5, 22, v5
	v_add_u32_e32 v5, v4, v5
	v_and_b32_e32 v5, 0xfffffc00, v5
	v_sub_u32_e32 v4, v4, v5
	v_lshrrev_b32_e32 v5, 4, v4
	v_bitop3_b32 v6, v5, v4, 32 bitop3:0x6c
	v_ashrrev_i32_e32 v5, 31, v7
	v_lshrrev_b32_e32 v5, 26, v5
	v_ashrrev_i32_e32 v4, 31, v4
	v_add_u32_e32 v5, v7, v5
	v_lshrrev_b32_e32 v4, 26, v4
	v_ashrrev_i32_e32 v5, 6, v5
	v_add_u32_e32 v4, v6, v4
	v_lshlrev_b32_e32 v8, 3, v5
	v_ashrrev_i32_e32 v4, 6, v4
	v_and_b32_e32 v8, -16, v8
	v_add_u32_e32 v8, v4, v8
	v_and_b32_e32 v9, 3, v4
	v_lshrrev_b32_e32 v10, 2, v8
	v_lshlrev_b32_e32 v11, 1, v8
	v_and_or_b32 v9, v8, s0, v9
	v_and_b32_e32 v10, 4, v10
	v_and_b32_e32 v11, 24, v11
	v_or3_b32 v9, v9, v10, v11
	v_mul_i32_i24_e32 v11, 64, v4
	s_ashr_i32 s9, s8, 6
	v_sub_u32_e32 v6, v6, v11
	s_ashr_i32 s22, s8, 8
	s_lshl_b32 s23, s9, 10
	v_lshlrev_b32_e32 v10, 5, v5
	v_ashrrev_i16_sdwa v6, v248, sext(v6) dst_sel:DWORD dst_unused:UNUSED_PAD src0_sel:DWORD src1_sel:BYTE_0
	v_readlane_b32 s0, v255, 25
	v_and_b32_e32 v10, 32, v10
	v_bfe_i32 v6, v6, 0, 16
	v_readlane_b32 s1, v255, 26
	s_add_u32 s10, s12, s0
	v_add_lshl_u32 v10, v10, v6, 1
	s_addc_u32 s11, s13, s1
	s_add_i32 s26, s23, 0
	v_lshl_add_u32 v146, v9, 11, v10
	s_add_i32 m0, s26, 0x10000
	v_lshl_add_u32 v148, v8, 11, v10
	global_load_lds_dwordx4 v146, s[10:11]
	s_add_i32 m0, s26, 0x12000
	s_add_u32 s0, s10, 0x40000
	global_load_lds_dwordx4 v142, s[10:11]
	s_addc_u32 s1, s11, 0
	s_add_i32 m0, s26, 0x14000
	s_add_i32 s33, s26, 0x2000
	global_load_lds_dwordx4 v146, s[0:1]
	s_add_i32 m0, s26, 0x16000
	s_add_i32 s38, s26, 0x4000
	global_load_lds_dwordx4 v142, s[0:1]
	v_readlane_b32 s0, v255, 27
	s_mov_b32 m0, s26
	v_readlane_b32 s1, v255, 28
	s_add_i32 s39, s26, 0x6000
	s_cmp_eq_u32 s22, 1
	s_nop 2
	global_load_lds_dwordx4 v148, s[0:1]
	s_mov_b32 m0, s33
	s_nop 0
	global_load_lds_dwordx4 v144, s[0:1]
	v_readlane_b32 s0, v255, 29
	s_mov_b32 m0, s38
	v_readlane_b32 s1, v255, 30
	s_nop 4
	global_load_lds_dwordx4 v148, s[0:1]
	s_mov_b32 m0, s39
	s_nop 0
	global_load_lds_dwordx4 v144, s[0:1]
	s_cselect_b64 s[0:1], -1, 0
	s_cmp_lg_u32 s22, 1
	s_cbranch_scc1 .LBB0_671
	s_barrier

;     f32x4 p[2][4];
; #pragma unroll
;     for (int ai = 0; ai < 2; ++ai)
; #pragma unroll
;         for (int m = 0; m < 4; ++m) { const size_t r = (size_t)(u.pm * BM + ai * HALF + wr * 64 + m * 16 + fr); p[ai][m] = *(const f32x4*)(ssq + ((size_t)fq * T + r) * 4); }
; #pragma unroll
;     for (int ai = 0; ai < 2; ++ai)
; #pragma unroll
;         for (int m = 0; m < 4; ++m) { float sq = (p[ai][m].x + p[ai][m].y) + (p[ai][m].z + p[ai][m].w);
;             sq += __shfl_xor(sq, 16); sq += __shfl_xor(sq, 32);
.LBB0_680:
	v_mov_b32_e32 v0, v246
	s_mov_b32 s10, s22
	s_mov_b32 s48, s52
	s_lshl_b32 s25, s57, 8
	s_lshl_b32 s43, s10, 6
	v_and_b32_e32 v156, 15, v0
	s_add_i32 s10, s43, s25
	v_bfe_u32 v157, v0, 4, 2
	v_or_b32_e32 v130, s10, v156
	v_lshlrev_b32_e32 v0, 15, v157
	v_ashrrev_i32_e32 v131, 31, v130
	s_cmp_eq_u32 s57, s100
	s_cselect_b64 s[98:99], -1, 0
	s_mov_b32 s100, s57
	s_cbranch_scc1 .Lrc1_skip
	v_lshl_add_u64 v[132:133], v[130:131], 0, v[0:1]
	v_lshl_add_u64 v[132:133], v[132:133], 4, s[70:71]
	global_load_dwordx4 v[158:161], v[132:133], off
	v_or_b32_e32 v132, 16, v130
	v_ashrrev_i32_e32 v133, 31, v132
	v_lshl_add_u64 v[132:133], v[132:133], 0, v[0:1]
	v_lshl_add_u64 v[132:133], v[132:133], 4, s[70:71]
	global_load_dwordx4 v[162:165], v[132:133], off
	v_or_b32_e32 v132, 32, v130
	v_ashrrev_i32_e32 v133, 31, v132
	v_lshl_add_u64 v[132:133], v[132:133], 0, v[0:1]
	v_lshl_add_u64 v[132:133], v[132:133], 4, s[70:71]
	global_load_dwordx4 v[176:179], v[132:133], off
	v_or_b32_e32 v132, 48, v130
	v_ashrrev_i32_e32 v133, 31, v132
	v_lshl_add_u64 v[132:133], v[132:133], 0, v[0:1]
	v_lshl_add_u64 v[132:133], v[132:133], 4, s[70:71]
	global_load_dwordx4 v[180:183], v[132:133], off
	v_add_u32_e32 v132, 0x80, v130
	v_ashrrev_i32_e32 v133, 31, v132
	v_lshl_add_u64 v[132:133], v[132:133], 0, v[0:1]
	v_lshl_add_u64 v[132:133], v[132:133], 4, s[70:71]
	global_load_dwordx4 v[184:187], v[132:133], off
	v_add_u32_e32 v132, 0x90, v130
	v_ashrrev_i32_e32 v133, 31, v132
	v_lshl_add_u64 v[132:133], v[132:133], 0, v[0:1]
	v_lshl_add_u64 v[132:133], v[132:133], 4, s[70:71]
	global_load_dwordx4 v[138:141], v[132:133], off
	v_add_u32_e32 v132, 0xa0, v130
	v_add_u32_e32 v130, 0xb0, v130
	v_ashrrev_i32_e32 v133, 31, v132
	v_ashrrev_i32_e32 v131, 31, v130
	v_lshl_add_u64 v[132:133], v[132:133], 0, v[0:1]
	v_lshl_add_u64 v[130:131], v[130:131], 0, v[0:1]
	v_lshl_add_u64 v[132:133], v[132:133], 4, s[70:71]
	v_lshl_add_u64 v[130:131], v[130:131], 4, s[70:71]
	global_load_dwordx4 v[134:137], v[132:133], off
	global_load_dwordx4 v[130:133], v[130:131], off
.Lrc1_skip:
	v_and_b32_e32 v166, 64, v249
	v_xor_b32_e32 v0, 16, v249
	v_add_u32_e32 v166, 64, v166
	v_cmp_lt_i32_e32 vcc, v0, v166
	s_mov_b64 s[10:11], -1
	s_cmp_gt_i32 s56, 3
	v_cndmask_b32_e32 v0, v249, v0, vcc
	v_lshlrev_b32_e32 v172, 2, v0
	v_xor_b32_e32 v0, 32, v249
	v_cmp_lt_i32_e32 vcc, v0, v166
	s_mov_b32 s94, s96
	s_waitcnt vmcnt(0)
	v_mov_b32_e32 v166, v159
	v_mov_b32_e32 v167, v160
	v_mov_b32_e32 v159, v161
	v_pk_add_f32 v[158:159], v[166:167], v[158:159]
	v_cndmask_b32_e32 v0, v249, v0, vcc
	v_mov_b32_e32 v160, v163
	v_mov_b32_e32 v161, v164
	v_mov_b32_e32 v163, v165
	v_pk_add_f32 v[160:161], v[160:161], v[162:163]
	v_lshlrev_b32_e32 v173, 2, v0
	v_mov_b32_e32 v162, v177
	v_mov_b32_e32 v163, v178
	v_mov_b32_e32 v177, v179
	v_pk_add_f32 v[162:163], v[162:163], v[176:177]
	v_add_f32_e32 v0, v158, v159
	v_mov_b32_e32 v164, v181
	v_mov_b32_e32 v165, v182
	v_mov_b32_e32 v181, v183
	v_pk_add_f32 v[164:165], v[164:165], v[180:181]
	v_add_f32_e32 v159, v160, v161
	v_mov_b32_e32 v166, v185
	v_mov_b32_e32 v167, v186
	v_mov_b32_e32 v185, v187
	v_pk_add_f32 v[166:167], v[166:167], v[184:185]
	v_add_f32_e32 v161, v162, v163
	v_mov_b32_e32 v176, v139
	v_mov_b32_e32 v177, v140
	v_mov_b32_e32 v139, v141
	v_pk_add_f32 v[138:139], v[176:177], v[138:139]
	v_add_f32_e32 v163, v164, v165
	v_add_f32_e32 v165, v166, v167
	v_add_f32_e32 v138, v138, v139
	ds_bpermute_b32 v158, v172, v0
	ds_bpermute_b32 v160, v172, v159
	v_mov_b32_e32 v140, v135
	v_mov_b32_e32 v141, v136
	v_mov_b32_e32 v135, v137
	v_mov_b32_e32 v136, v131
	v_mov_b32_e32 v137, v132
	v_mov_b32_e32 v131, v133
	v_pk_add_f32 v[134:135], v[140:141], v[134:135]
	v_pk_add_f32 v[130:131], v[136:137], v[130:131]
	v_add_f32_e32 v134, v134, v135
	v_add_f32_e32 v130, v130, v131
	ds_bpermute_b32 v162, v172, v161
	ds_bpermute_b32 v164, v172, v163
	ds_bpermute_b32 v166, v172, v165
	ds_bpermute_b32 v139, v172, v138
	ds_bpermute_b32 v135, v172, v134
	ds_bpermute_b32 v131, v172, v130
	s_waitcnt lgkmcnt(7)
	v_add_f32_e32 v0, v0, v158
	s_waitcnt lgkmcnt(6)
	v_add_f32_e32 v159, v159, v160
	s_waitcnt lgkmcnt(5)
	v_add_f32_e32 v161, v161, v162
	s_waitcnt lgkmcnt(4)
	v_add_f32_e32 v163, v163, v164
	s_waitcnt lgkmcnt(3)
	v_add_f32_e32 v165, v165, v166
	s_waitcnt lgkmcnt(2)
	v_add_f32_e32 v138, v138, v139
	s_waitcnt lgkmcnt(1)
	v_add_f32_e32 v134, v134, v135
	s_waitcnt lgkmcnt(0)
	v_add_f32_e32 v136, v130, v131
	ds_bpermute_b32 v158, v173, v0
	ds_bpermute_b32 v160, v173, v159
	ds_bpermute_b32 v162, v173, v161
	ds_bpermute_b32 v164, v173, v163
	ds_bpermute_b32 v166, v173, v165
	ds_bpermute_b32 v139, v173, v138
	ds_bpermute_b32 v135, v173, v134
	ds_bpermute_b32 v137, v173, v136
	s_cbranch_scc0 .LBB0_694
	s_cmp_gt_u32 s56, 5
	s_cbranch_scc0 .LBB0_691
	s_cmp_gt_u32 s56, 7
	s_cbranch_scc0 .LBB0_688
	s_cmp_gt_u32 s56, 9
	s_cbranch_scc0 .LBB0_685
	s_cmp_eq_u32 s56, 10
	s_movk_i32 s10, 0x1100
	s_cselect_b32 s50, 0x1000, s10
	s_mov_b64 s[10:11], 0

;     ...
;         for (int m = 0; m < 4; ++m) { float sq = (p[ai][m].x + p[ai][m].y) + (p[ai][m].z + p[ai][m].w);
;             sq += __shfl_xor(sq, 16); sq += __shfl_xor(sq, 32);
;             const float rs = __builtin_amdgcn_rsqf(sq * (1.0f / DM) + EPS) * mul;
; #pragma unroll
;             for (int bj = 0; bj < 2; ++bj)
; #pragma unroll
;                 for (int n = 0; n < 2; ++n) acc[ai][bj][m][n] = acc[ai][bj][m][n] * rs; }
.LBB0_696:
	s_waitcnt lgkmcnt(7)
	v_add_f32_e32 v0, v0, v158
	v_fmamk_f32 v0, v0, 0x3a800000, v247
	v_rsq_f32_e32 v0, v0
	s_nop 0
	v_cndmask_b32_e64 v0, v0, v226, s[98:99]
	v_mov_b32_e32 v226, v0
	s_ashr_i32 s51, s50, 31
	s_lshl_b32 s48, s48, 6
	s_ashr_i32 s49, s48, 31
	v_mul_f32_e32 v0, 0xbfb8aa3b, v0
	v_pk_mul_f32 v[176:177], v[122:123], v[0:1] op_sel_hi:[1,0]
	v_pk_mul_f32 v[122:123], v[112:113], v[0:1] op_sel_hi:[1,0]
	s_waitcnt lgkmcnt(6)
	v_add_f32_e32 v112, v159, v160
	v_fmamk_f32 v112, v112, 0x3a800000, v247
	v_rsq_f32_e32 v112, v112
	s_nop 0
	v_cndmask_b32_e64 v112, v112, v227, s[98:99]
	v_mov_b32_e32 v227, v112
	v_pk_mul_f32 v[132:133], v[128:129], v[0:1] op_sel_hi:[1,0]
	v_pk_mul_f32 v[140:141], v[126:127], v[0:1] op_sel_hi:[1,0]
	v_pk_mul_f32 v[130:131], v[124:125], v[0:1] op_sel_hi:[1,0]
	v_pk_mul_f32 v[128:129], v[110:111], v[0:1] op_sel_hi:[1,0]
	v_pk_mul_f32 v[124:125], v[108:109], v[0:1] op_sel_hi:[1,0]
	v_pk_mul_f32 v[126:127], v[106:107], v[0:1] op_sel_hi:[1,0]
	v_mul_f32_e32 v0, 0xbfb8aa3b, v112
	v_pk_mul_f32 v[106:107], v[96:97], v[0:1] op_sel_hi:[1,0]
	s_waitcnt lgkmcnt(5)
	v_add_f32_e32 v96, v161, v162
	v_fmamk_f32 v96, v96, 0x3a800000, v247
	v_rsq_f32_e32 v96, v96
	s_nop 0
	v_cndmask_b32_e64 v96, v96, v228, s[98:99]
	v_mov_b32_e32 v228, v96
	v_pk_mul_f32 v[120:121], v[120:121], v[0:1] op_sel_hi:[1,0]
	v_pk_mul_f32 v[118:119], v[118:119], v[0:1] op_sel_hi:[1,0]
	v_pk_mul_f32 v[116:117], v[116:117], v[0:1] op_sel_hi:[1,0]
	v_pk_mul_f32 v[114:115], v[114:115], v[0:1] op_sel_hi:[1,0]
	v_pk_mul_f32 v[112:113], v[94:95], v[0:1] op_sel_hi:[1,0]
	v_pk_mul_f32 v[108:109], v[92:93], v[0:1] op_sel_hi:[1,0]
	v_pk_mul_f32 v[110:111], v[90:91], v[0:1] op_sel_hi:[1,0]
	v_mul_f32_e32 v0, 0xbfb8aa3b, v96
	v_pk_mul_f32 v[90:91], v[80:81], v[0:1] op_sel_hi:[1,0]
	s_waitcnt lgkmcnt(4)
	v_add_f32_e32 v80, v163, v164
	v_fmamk_f32 v80, v80, 0x3a800000, v247
	v_rsq_f32_e32 v80, v80
	s_nop 0
	v_cndmask_b32_e64 v80, v80, v229, s[98:99]
	v_mov_b32_e32 v229, v80
	v_pk_mul_f32 v[104:105], v[104:105], v[0:1] op_sel_hi:[1,0]
	v_pk_mul_f32 v[102:103], v[102:103], v[0:1] op_sel_hi:[1,0]
	v_pk_mul_f32 v[100:101], v[100:101], v[0:1] op_sel_hi:[1,0]
	v_pk_mul_f32 v[98:99], v[98:99], v[0:1] op_sel_hi:[1,0]
	v_pk_mul_f32 v[96:97], v[78:79], v[0:1] op_sel_hi:[1,0]
	v_pk_mul_f32 v[92:93], v[76:77], v[0:1] op_sel_hi:[1,0]
	v_pk_mul_f32 v[94:95], v[74:75], v[0:1] op_sel_hi:[1,0]
	v_mul_f32_e32 v0, 0xbfb8aa3b, v80
	v_pk_mul_f32 v[74:75], v[72:73], v[0:1] op_sel_hi:[1,0]
	s_waitcnt lgkmcnt(3)
	v_add_f32_e32 v72, v165, v166
	v_fmamk_f32 v72, v72, 0x3a800000, v247
	v_rsq_f32_e32 v72, v72
	s_nop 0
	v_cndmask_b32_e64 v72, v72, v230, s[98:99]
	v_mov_b32_e32 v230, v72
	v_pk_mul_f32 v[88:89], v[88:89], v[0:1] op_sel_hi:[1,0]
	v_pk_mul_f32 v[86:87], v[86:87], v[0:1] op_sel_hi:[1,0]
	v_pk_mul_f32 v[84:85], v[84:85], v[0:1] op_sel_hi:[1,0]
	v_pk_mul_f32 v[82:83], v[82:83], v[0:1] op_sel_hi:[1,0]
	v_pk_mul_f32 v[80:81], v[70:71], v[0:1] op_sel_hi:[1,0]
	v_pk_mul_f32 v[76:77], v[68:69], v[0:1] op_sel_hi:[1,0]
	v_pk_mul_f32 v[78:79], v[66:67], v[0:1] op_sel_hi:[1,0]
	v_mul_f32_e32 v0, 0xbfb8aa3b, v72
	v_pk_mul_f32 v[70:71], v[58:59], v[0:1] op_sel_hi:[1,0]
	v_pk_mul_f32 v[58:59], v[48:49], v[0:1] op_sel_hi:[1,0]
	s_waitcnt lgkmcnt(2)
	v_add_f32_e32 v48, v138, v139
	v_fmamk_f32 v48, v48, 0x3a800000, v247
	v_rsq_f32_e32 v48, v48
	s_nop 0
	v_cndmask_b32_e64 v48, v48, v231, s[98:99]
	v_mov_b32_e32 v231, v48
	v_pk_mul_f32 v[68:69], v[64:65], v[0:1] op_sel_hi:[1,0]
	v_pk_mul_f32 v[72:73], v[62:63], v[0:1] op_sel_hi:[1,0]
	v_pk_mul_f32 v[66:67], v[60:61], v[0:1] op_sel_hi:[1,0]
	v_pk_mul_f32 v[64:65], v[46:47], v[0:1] op_sel_hi:[1,0]
	v_pk_mul_f32 v[60:61], v[44:45], v[0:1] op_sel_hi:[1,0]
	v_pk_mul_f32 v[62:63], v[42:43], v[0:1] op_sel_hi:[1,0]
	v_mul_f32_e32 v0, 0xbfb8aa3b, v48
	v_pk_mul_f32 v[42:43], v[32:33], v[0:1] op_sel_hi:[1,0]
	s_waitcnt lgkmcnt(1)
	v_add_f32_e32 v32, v134, v135
	v_fmamk_f32 v32, v32, 0x3a800000, v247
	v_rsq_f32_e32 v32, v32
	s_nop 0
	v_cndmask_b32_e64 v32, v32, v232, s[98:99]
	v_mov_b32_e32 v232, v32
	v_pk_mul_f32 v[56:57], v[56:57], v[0:1] op_sel_hi:[1,0]
	v_pk_mul_f32 v[54:55], v[54:55], v[0:1] op_sel_hi:[1,0]
	v_pk_mul_f32 v[52:53], v[52:53], v[0:1] op_sel_hi:[1,0]
	v_pk_mul_f32 v[50:51], v[50:51], v[0:1] op_sel_hi:[1,0]
	v_pk_mul_f32 v[48:49], v[30:31], v[0:1] op_sel_hi:[1,0]
	v_pk_mul_f32 v[44:45], v[28:29], v[0:1] op_sel_hi:[1,0]
	v_pk_mul_f32 v[46:47], v[26:27], v[0:1] op_sel_hi:[1,0]
	v_mul_f32_e32 v0, 0xbfb8aa3b, v32
	v_pk_mul_f32 v[26:27], v[16:17], v[0:1] op_sel_hi:[1,0]
	s_waitcnt lgkmcnt(0)
;     ...
;             const float rs = __builtin_amdgcn_rsqf(sq * (1.0f / DM) + EPS) * mul;
; #pragma unroll
;             for (int bj = 0; bj < 2; ++bj)
; #pragma unroll
;                 for (int n = 0; n < 2; ++n) acc[ai][bj][m][n] = acc[ai][bj][m][n] * rs; }
;     __device__ __forceinline__ void operator()(f32x4 (&acc)[2][2][4][2], const Unit& u, int wr, int wc, int fr, int fq) const {
;     ...
;                     if (MODE == 1) {
;                         unsigned g0 = 0u, g1 = 0u;
; #pragma unroll
;                         for (int e = 0; e < 4; ++e) { g0 = __builtin_amdgcn_cvt_pk_u8_f32(fmaxf(floorf(255.f * __builtin_amdgcn_rcpf(1.0f + __builtin_amdgcn_exp2f(v0[e])) + 0.5f), 1.f), e, g0);
;                                                       g1 = __builtin_amdgcn_cvt_pk_u8_f32(fmaxf(floorf(255.f * __builtin_amdgcn_rcpf(1.0f + __builtin_amdgcn_exp2f(v1[e])) + 0.5f), 1.f), e, g1); }
;                         *(u32x2*)((unsigned char*)O + ((size_t)(row0 + ai * HALF + m * 16) * ldc + colt) * 2 + bj * HALF + wc * 32 + 8 * fq) = (u32x2){g0, g1};
	v_add_f32_e32 v16, v136, v137
	v_fmamk_f32 v16, v16, 0x3a800000, v247
	v_rsq_f32_e32 v16, v16
	s_nop 0
	v_cndmask_b32_e64 v16, v16, v233, s[98:99]
	v_mov_b32_e32 v233, v16
	v_pk_mul_f32 v[40:41], v[40:41], v[0:1] op_sel_hi:[1,0]
	v_pk_mul_f32 v[38:39], v[38:39], v[0:1] op_sel_hi:[1,0]
	v_pk_mul_f32 v[36:37], v[36:37], v[0:1] op_sel_hi:[1,0]
	v_pk_mul_f32 v[34:35], v[34:35], v[0:1] op_sel_hi:[1,0]
	v_pk_mul_f32 v[32:33], v[14:15], v[0:1] op_sel_hi:[1,0]
	v_pk_mul_f32 v[28:29], v[12:13], v[0:1] op_sel_hi:[1,0]
	v_pk_mul_f32 v[30:31], v[10:11], v[0:1] op_sel_hi:[1,0]
	v_mul_f32_e32 v0, 0xbfb8aa3b, v16
	v_pk_mul_f32 v[14:15], v[18:19], v[0:1] op_sel_hi:[1,0]
	v_exp_f32_e32 v18, v140
	v_pk_mul_f32 v[10:11], v[20:21], v[0:1] op_sel_hi:[1,0]
	v_exp_f32_e32 v21, v141
	v_pk_mul_f32 v[16:17], v[22:23], v[0:1] op_sel_hi:[1,0]
	v_or_b32_e32 v19, s43, v156
	v_add_f32_e32 v18, 1.0, v18
	v_exp_f32_e32 v22, v177
	v_add_u32_e32 v20, s25, v19
	v_rcp_f32_e32 v18, v18
	v_exp_f32_e32 v19, v176
	v_add_f32_e32 v21, 1.0, v21
	v_rcp_f32_e32 v21, v21
	v_add_f32_e32 v22, 1.0, v22
	v_fma_f32 v18, v18, s66, 0.5
	v_add_f32_e32 v19, 1.0, v19
	v_rcp_f32_e32 v22, v22
	v_exp_f32_e32 v23, v132
	v_floor_f32_e32 v18, v18
	v_rcp_f32_e32 v19, v19
	v_fma_f32 v21, v21, s66, 0.5
	v_max_f32_e32 v18, 1.0, v18
	v_floor_f32_e32 v21, v21
	v_cvt_pk_u8_f32 v18, v18, 0, 0
	v_max_f32_e32 v21, 1.0, v21
	v_cvt_pk_u8_f32 v18, v21, 1, v18
	v_fma_f32 v21, v22, s66, 0.5
	v_add_f32_e32 v22, 1.0, v23
	v_fma_f32 v19, v19, s66, 0.5
	v_rcp_f32_e32 v22, v22
	v_exp_f32_e32 v23, v130
	v_floor_f32_e32 v19, v19
	v_max_f32_e32 v19, 1.0, v19
	v_floor_f32_e32 v21, v21
	v_cvt_pk_u8_f32 v19, v19, 0, 0
	v_max_f32_e32 v21, 1.0, v21
	v_cvt_pk_u8_f32 v19, v21, 1, v19
	v_fma_f32 v21, v22, s66, 0.5
	v_add_f32_e32 v22, 1.0, v23
	v_rcp_f32_e32 v22, v22
	v_exp_f32_e32 v23, v133
	v_floor_f32_e32 v21, v21
	v_max_f32_e32 v21, 1.0, v21
	v_cvt_pk_u8_f32 v18, v21, 2, v18
	v_fma_f32 v21, v22, s66, 0.5
	v_add_f32_e32 v22, 1.0, v23
	v_rcp_f32_e32 v22, v22
	v_exp_f32_e32 v23, v131
	v_floor_f32_e32 v21, v21
	v_max_f32_e32 v21, 1.0, v21
	v_cvt_pk_u8_f32 v19, v21, 2, v19
	v_fma_f32 v21, v22, s66, 0.5
	v_add_f32_e32 v22, 1.0, v23
	v_rcp_f32_e32 v23, v22
	v_floor_f32_e32 v21, v21
	v_max_f32_e32 v21, 1.0, v21
	v_cvt_pk_u8_f32 v22, v21, 3, v18
	v_fma_f32 v18, v23, s66, 0.5
	v_floor_f32_e32 v18, v18
	v_max_f32_e32 v18, 1.0, v18
	v_cvt_pk_u8_f32 v23, v18, 3, v19
	v_mov_b64_e32 v[18:19], s[50:51]
	s_movk_i32 s25, 0x1200
	v_pk_mul_f32 v[12:13], v[24:25], v[0:1] op_sel_hi:[1,0]
	v_mad_i64_i32 v[24:25], s[10:11], v20, s25, v[18:19]
	v_lshl_add_u64 v[24:25], v[24:25], 1, s[68:69]
	v_pk_mul_f32 v[8:9], v[8:9], v[0:1] op_sel_hi:[1,0]
	v_pk_mul_f32 v[6:7], v[6:7], v[0:1] op_sel_hi:[1,0]
	v_pk_mul_f32 v[4:5], v[4:5], v[0:1] op_sel_hi:[1,0]
	v_pk_mul_f32 v[2:3], v[2:3], v[0:1] op_sel_hi:[1,0]
	v_lshlrev_b32_e32 v0, 4, v157
	v_lshl_add_u64 v[24:25], v[24:25], 0, s[48:49]
	v_exp_f32_e32 v21, v128
	v_lshl_add_u64 v[24:25], v[24:25], 0, v[0:1]
	v_exp_f32_e32 v126, v126
	v_mov_b32_e32 v240, v22
	v_mov_b32_e32 v241, v23
	v_exp_f32_e32 v23, v129
	v_add_f32_e32 v21, 1.0, v21
	v_add_f32_e32 v22, 1.0, v126
	v_exp_f32_e32 v126, v127
	v_rcp_f32_e32 v21, v21
	v_add_f32_e32 v23, 1.0, v23
	v_rcp_f32_e32 v23, v23
	v_exp_f32_e32 v122, v122
	v_rcp_f32_e32 v22, v22
	v_add_f32_e32 v126, 1.0, v126
	v_fma_f32 v21, v21, s66, 0.5
	v_rcp_f32_e32 v126, v126
	v_floor_f32_e32 v21, v21
	v_fma_f32 v23, v23, s66, 0.5
	v_max_f32_e32 v21, 1.0, v21
	v_floor_f32_e32 v23, v23
	v_add_f32_e32 v122, 1.0, v122
	v_cvt_pk_u8_f32 v21, v21, 0, 0
	v_fma_f32 v22, v22, s66, 0.5
	v_max_f32_e32 v23, 1.0, v23
	v_rcp_f32_e32 v122, v122
	v_exp_f32_e32 v124, v124
	v_floor_f32_e32 v22, v22
	v_cvt_pk_u8_f32 v21, v23, 1, v21
	v_fma_f32 v23, v126, s66, 0.5
	v_max_f32_e32 v22, 1.0, v22
	v_floor_f32_e32 v23, v23
	v_cvt_pk_u8_f32 v22, v22, 0, 0
	v_max_f32_e32 v23, 1.0, v23
	v_cvt_pk_u8_f32 v22, v23, 1, v22
	v_fma_f32 v23, v122, s66, 0.5
	v_add_f32_e32 v122, 1.0, v124
	v_rcp_f32_e32 v122, v122
	v_exp_f32_e32 v123, v123
	v_floor_f32_e32 v23, v23
	v_max_f32_e32 v23, 1.0, v23
	v_cvt_pk_u8_f32 v21, v23, 2, v21
	v_fma_f32 v23, v122, s66, 0.5
	v_add_f32_e32 v122, 1.0, v123
	v_rcp_f32_e32 v122, v122
	v_exp_f32_e32 v123, v125
	v_floor_f32_e32 v23, v23
	v_max_f32_e32 v23, 1.0, v23
	v_cvt_pk_u8_f32 v23, v23, 2, v22
	v_fma_f32 v22, v122, s66, 0.5
	v_add_f32_e32 v122, 1.0, v123
	v_rcp_f32_e32 v122, v122
	v_floor_f32_e32 v22, v22
	v_max_f32_e32 v22, 1.0, v22
	v_cvt_pk_u8_f32 v22, v22, 3, v21
	v_fma_f32 v21, v122, s66, 0.5
	v_floor_f32_e32 v21, v21
	v_max_f32_e32 v21, 1.0, v21
	v_exp_f32_e32 v118, v118
	v_cvt_pk_u8_f32 v23, v21, 3, v23
	v_mov_b32_e32 v242, v22
	v_mov_b32_e32 v243, v23
	global_store_dwordx4 v[24:25], v[240:243], off
	v_exp_f32_e32 v23, v119
	v_add_f32_e32 v21, 1.0, v118
	v_exp_f32_e32 v25, v115
	v_rcp_f32_e32 v21, v21
	v_exp_f32_e32 v22, v114
	v_add_f32_e32 v23, 1.0, v23
	v_rcp_f32_e32 v23, v23
	v_add_f32_e32 v25, 1.0, v25
	v_fma_f32 v21, v21, s66, 0.5
	v_add_f32_e32 v22, 1.0, v22
	v_rcp_f32_e32 v25, v25
	v_exp_f32_e32 v114, v120
	v_floor_f32_e32 v21, v21
	v_rcp_f32_e32 v22, v22
	v_fma_f32 v23, v23, s66, 0.5
	v_max_f32_e32 v21, 1.0, v21
	v_floor_f32_e32 v23, v23
	v_cvt_pk_u8_f32 v21, v21, 0, 0
	v_max_f32_e32 v23, 1.0, v23
	v_cvt_pk_u8_f32 v21, v23, 1, v21
	v_fma_f32 v23, v25, s66, 0.5
	v_add_f32_e32 v25, 1.0, v114
	v_fma_f32 v22, v22, s66, 0.5
	v_rcp_f32_e32 v25, v25
	v_exp_f32_e32 v114, v116
	v_floor_f32_e32 v22, v22
	v_max_f32_e32 v22, 1.0, v22
	v_floor_f32_e32 v23, v23
	v_cvt_pk_u8_f32 v22, v22, 0, 0
	v_max_f32_e32 v23, 1.0, v23
	v_cvt_pk_u8_f32 v22, v23, 1, v22
	v_fma_f32 v23, v25, s66, 0.5
;     __device__ __forceinline__ void operator()(f32x4 (&acc)[2][2][4][2], const Unit& u, int wr, int wc, int fr, int fq) const {
;     ...
;                     if (MODE == 1) {
;                         unsigned g0 = 0u, g1 = 0u;
; #pragma unroll
;                         for (int e = 0; e < 4; ++e) { g0 = __builtin_amdgcn_cvt_pk_u8_f32(fmaxf(floorf(255.f * __builtin_amdgcn_rcpf(1.0f + __builtin_amdgcn_exp2f(v0[e])) + 0.5f), 1.f), e, g0);
;                                                       g1 = __builtin_amdgcn_cvt_pk_u8_f32(fmaxf(floorf(255.f * __builtin_amdgcn_rcpf(1.0f + __builtin_amdgcn_exp2f(v1[e])) + 0.5f), 1.f), e, g1); }
;                         *(u32x2*)((unsigned char*)O + ((size_t)(row0 + ai * HALF + m * 16) * ldc + colt) * 2 + bj * HALF + wc * 32 + 8 * fq) = (u32x2){g0, g1};
	v_add_f32_e32 v25, 1.0, v114
	v_rcp_f32_e32 v25, v25
	v_exp_f32_e32 v114, v121
	v_floor_f32_e32 v23, v23
	v_max_f32_e32 v23, 1.0, v23
	v_cvt_pk_u8_f32 v21, v23, 2, v21
	v_fma_f32 v23, v25, s66, 0.5
	v_add_f32_e32 v25, 1.0, v114
	v_rcp_f32_e32 v25, v25
	v_exp_f32_e32 v114, v117
	v_floor_f32_e32 v23, v23
	v_max_f32_e32 v23, 1.0, v23
	v_cvt_pk_u8_f32 v23, v23, 2, v22
	v_fma_f32 v22, v25, s66, 0.5
	v_add_f32_e32 v25, 1.0, v114
	v_rcp_f32_e32 v25, v25
	v_floor_f32_e32 v22, v22
	v_or_b32_e32 v24, 16, v20
	v_max_f32_e32 v22, 1.0, v22
	v_cvt_pk_u8_f32 v22, v22, 3, v21
	v_fma_f32 v21, v25, s66, 0.5
	v_mad_i64_i32 v[24:25], s[10:11], v24, s25, v[18:19]
	v_floor_f32_e32 v21, v21
	v_lshl_add_u64 v[24:25], v[24:25], 1, s[68:69]
	v_max_f32_e32 v21, 1.0, v21
	v_lshl_add_u64 v[24:25], v[24:25], 0, s[48:49]
	v_cvt_pk_u8_f32 v23, v21, 3, v23
	v_exp_f32_e32 v21, v112
	v_lshl_add_u64 v[24:25], v[24:25], 0, v[0:1]
	v_exp_f32_e32 v110, v110
	v_mov_b32_e32 v236, v22
	v_mov_b32_e32 v237, v23
	v_exp_f32_e32 v23, v113
	v_add_f32_e32 v21, 1.0, v21
	v_add_f32_e32 v22, 1.0, v110
	v_exp_f32_e32 v110, v111
	v_rcp_f32_e32 v21, v21
	v_add_f32_e32 v23, 1.0, v23
	v_rcp_f32_e32 v23, v23
	v_exp_f32_e32 v106, v106
	v_rcp_f32_e32 v22, v22
	v_add_f32_e32 v110, 1.0, v110
	v_fma_f32 v21, v21, s66, 0.5
	v_rcp_f32_e32 v110, v110
	v_floor_f32_e32 v21, v21
	v_fma_f32 v23, v23, s66, 0.5
	v_max_f32_e32 v21, 1.0, v21
	v_floor_f32_e32 v23, v23
	v_add_f32_e32 v106, 1.0, v106
	v_cvt_pk_u8_f32 v21, v21, 0, 0
	v_fma_f32 v22, v22, s66, 0.5
	v_max_f32_e32 v23, 1.0, v23
	v_rcp_f32_e32 v106, v106
	v_exp_f32_e32 v108, v108
	v_floor_f32_e32 v22, v22
	v_cvt_pk_u8_f32 v21, v23, 1, v21
	v_fma_f32 v23, v110, s66, 0.5
	v_max_f32_e32 v22, 1.0, v22
	v_floor_f32_e32 v23, v23
	v_cvt_pk_u8_f32 v22, v22, 0, 0
	v_max_f32_e32 v23, 1.0, v23
	v_cvt_pk_u8_f32 v22, v23, 1, v22
	v_fma_f32 v23, v106, s66, 0.5
	v_add_f32_e32 v106, 1.0, v108
	v_rcp_f32_e32 v106, v106
	v_exp_f32_e32 v107, v107
	v_floor_f32_e32 v23, v23
	v_max_f32_e32 v23, 1.0, v23
	v_cvt_pk_u8_f32 v21, v23, 2, v21
	v_fma_f32 v23, v106, s66, 0.5
	v_add_f32_e32 v106, 1.0, v107
	v_rcp_f32_e32 v106, v106
	v_exp_f32_e32 v107, v109
	v_floor_f32_e32 v23, v23
	v_max_f32_e32 v23, 1.0, v23
	v_cvt_pk_u8_f32 v23, v23, 2, v22
	v_fma_f32 v22, v106, s66, 0.5
	v_add_f32_e32 v106, 1.0, v107
	v_rcp_f32_e32 v106, v106
	v_floor_f32_e32 v22, v22
	v_max_f32_e32 v22, 1.0, v22
	v_cvt_pk_u8_f32 v22, v22, 3, v21
	v_fma_f32 v21, v106, s66, 0.5
	v_floor_f32_e32 v21, v21
	v_max_f32_e32 v21, 1.0, v21
	v_exp_f32_e32 v102, v102
	v_cvt_pk_u8_f32 v23, v21, 3, v23
	v_mov_b32_e32 v238, v22
	v_mov_b32_e32 v239, v23
	global_store_dwordx4 v[24:25], v[236:239], off
	v_exp_f32_e32 v23, v103
	v_add_f32_e32 v21, 1.0, v102
	v_exp_f32_e32 v25, v99
	v_rcp_f32_e32 v21, v21
	v_exp_f32_e32 v22, v98
	v_add_f32_e32 v23, 1.0, v23
	v_rcp_f32_e32 v23, v23
	v_add_f32_e32 v25, 1.0, v25
	v_fma_f32 v21, v21, s66, 0.5
	v_add_f32_e32 v22, 1.0, v22
	v_rcp_f32_e32 v25, v25
	v_exp_f32_e32 v98, v104
	v_floor_f32_e32 v21, v21
	v_rcp_f32_e32 v22, v22
	v_fma_f32 v23, v23, s66, 0.5
	v_max_f32_e32 v21, 1.0, v21
	v_floor_f32_e32 v23, v23
	v_cvt_pk_u8_f32 v21, v21, 0, 0
	v_max_f32_e32 v23, 1.0, v23
	v_cvt_pk_u8_f32 v21, v23, 1, v21
	v_fma_f32 v23, v25, s66, 0.5
	v_add_f32_e32 v25, 1.0, v98
	v_fma_f32 v22, v22, s66, 0.5
	v_rcp_f32_e32 v25, v25
	v_exp_f32_e32 v98, v100
	v_floor_f32_e32 v22, v22
	v_max_f32_e32 v22, 1.0, v22
	v_floor_f32_e32 v23, v23
	v_cvt_pk_u8_f32 v22, v22, 0, 0
	v_max_f32_e32 v23, 1.0, v23
	v_cvt_pk_u8_f32 v22, v23, 1, v22
	v_fma_f32 v23, v25, s66, 0.5
	v_add_f32_e32 v25, 1.0, v98
	v_rcp_f32_e32 v25, v25
	v_exp_f32_e32 v98, v105
	v_floor_f32_e32 v23, v23
	v_max_f32_e32 v23, 1.0, v23
	v_cvt_pk_u8_f32 v21, v23, 2, v21
	v_fma_f32 v23, v25, s66, 0.5
	v_add_f32_e32 v25, 1.0, v98
	v_rcp_f32_e32 v25, v25
	v_exp_f32_e32 v98, v101
	v_floor_f32_e32 v23, v23
	v_max_f32_e32 v23, 1.0, v23
	v_cvt_pk_u8_f32 v23, v23, 2, v22
	v_fma_f32 v22, v25, s66, 0.5
	v_add_f32_e32 v25, 1.0, v98
	v_rcp_f32_e32 v25, v25
	v_floor_f32_e32 v22, v22
	v_or_b32_e32 v24, 32, v20
	v_max_f32_e32 v22, 1.0, v22
	v_cvt_pk_u8_f32 v22, v22, 3, v21
	v_fma_f32 v21, v25, s66, 0.5
	v_mad_i64_i32 v[24:25], s[10:11], v24, s25, v[18:19]
	v_floor_f32_e32 v21, v21
	v_lshl_add_u64 v[24:25], v[24:25], 1, s[68:69]
	v_max_f32_e32 v21, 1.0, v21
	v_lshl_add_u64 v[24:25], v[24:25], 0, s[48:49]
	v_cvt_pk_u8_f32 v23, v21, 3, v23
	v_exp_f32_e32 v21, v96
	v_lshl_add_u64 v[24:25], v[24:25], 0, v[0:1]
	v_exp_f32_e32 v94, v94
	v_mov_b32_e32 v240, v22
	v_mov_b32_e32 v241, v23
	v_exp_f32_e32 v23, v97
	v_add_f32_e32 v21, 1.0, v21
	v_add_f32_e32 v22, 1.0, v94
	v_exp_f32_e32 v94, v95
	v_rcp_f32_e32 v21, v21
	v_add_f32_e32 v23, 1.0, v23
	v_rcp_f32_e32 v23, v23
	v_exp_f32_e32 v90, v90
	v_rcp_f32_e32 v22, v22
	v_add_f32_e32 v94, 1.0, v94
	v_fma_f32 v21, v21, s66, 0.5
	v_rcp_f32_e32 v94, v94
	v_floor_f32_e32 v21, v21
	v_fma_f32 v23, v23, s66, 0.5
	v_max_f32_e32 v21, 1.0, v21
	v_floor_f32_e32 v23, v23
	v_add_f32_e32 v90, 1.0, v90
	v_cvt_pk_u8_f32 v21, v21, 0, 0
	v_fma_f32 v22, v22, s66, 0.5
	v_max_f32_e32 v23, 1.0, v23
	v_rcp_f32_e32 v90, v90
	v_exp_f32_e32 v92, v92
	v_floor_f32_e32 v22, v22
	v_cvt_pk_u8_f32 v21, v23, 1, v21
	v_fma_f32 v23, v94, s66, 0.5
	v_max_f32_e32 v22, 1.0, v22
	v_floor_f32_e32 v23, v23
	v_cvt_pk_u8_f32 v22, v22, 0, 0
	v_max_f32_e32 v23, 1.0, v23
	v_cvt_pk_u8_f32 v22, v23, 1, v22
	v_fma_f32 v23, v90, s66, 0.5
	v_add_f32_e32 v90, 1.0, v92
	v_rcp_f32_e32 v90, v90
	v_exp_f32_e32 v91, v91
	v_floor_f32_e32 v23, v23
	v_max_f32_e32 v23, 1.0, v23
	v_cvt_pk_u8_f32 v21, v23, 2, v21
	v_fma_f32 v23, v90, s66, 0.5
	v_add_f32_e32 v90, 1.0, v91
	v_rcp_f32_e32 v90, v90
;     __device__ __forceinline__ void operator()(f32x4 (&acc)[2][2][4][2], const Unit& u, int wr, int wc, int fr, int fq) const {
;     ...
;                     if (MODE == 1) {
;                         unsigned g0 = 0u, g1 = 0u;
; #pragma unroll
;                         for (int e = 0; e < 4; ++e) { g0 = __builtin_amdgcn_cvt_pk_u8_f32(fmaxf(floorf(255.f * __builtin_amdgcn_rcpf(1.0f + __builtin_amdgcn_exp2f(v0[e])) + 0.5f), 1.f), e, g0);
;                                                       g1 = __builtin_amdgcn_cvt_pk_u8_f32(fmaxf(floorf(255.f * __builtin_amdgcn_rcpf(1.0f + __builtin_amdgcn_exp2f(v1[e])) + 0.5f), 1.f), e, g1); }
;                         *(u32x2*)((unsigned char*)O + ((size_t)(row0 + ai * HALF + m * 16) * ldc + colt) * 2 + bj * HALF + wc * 32 + 8 * fq) = (u32x2){g0, g1};
	v_exp_f32_e32 v91, v93
	v_floor_f32_e32 v23, v23
	v_max_f32_e32 v23, 1.0, v23
	v_cvt_pk_u8_f32 v23, v23, 2, v22
	v_fma_f32 v22, v90, s66, 0.5
	v_add_f32_e32 v90, 1.0, v91
	v_rcp_f32_e32 v90, v90
	v_floor_f32_e32 v22, v22
	v_max_f32_e32 v22, 1.0, v22
	v_cvt_pk_u8_f32 v22, v22, 3, v21
	v_fma_f32 v21, v90, s66, 0.5
	v_floor_f32_e32 v21, v21
	v_max_f32_e32 v21, 1.0, v21
	v_exp_f32_e32 v86, v86
	v_cvt_pk_u8_f32 v23, v21, 3, v23
	v_mov_b32_e32 v242, v22
	v_mov_b32_e32 v243, v23
	global_store_dwordx4 v[24:25], v[240:243], off
	v_exp_f32_e32 v23, v87
	v_add_f32_e32 v21, 1.0, v86
	v_exp_f32_e32 v25, v83
	v_rcp_f32_e32 v21, v21
	v_exp_f32_e32 v22, v82
	v_add_f32_e32 v23, 1.0, v23
	v_rcp_f32_e32 v23, v23
	v_add_f32_e32 v25, 1.0, v25
	v_fma_f32 v21, v21, s66, 0.5
	v_add_f32_e32 v22, 1.0, v22
	v_rcp_f32_e32 v25, v25
	v_exp_f32_e32 v82, v88
	v_floor_f32_e32 v21, v21
	v_rcp_f32_e32 v22, v22
	v_fma_f32 v23, v23, s66, 0.5
	v_max_f32_e32 v21, 1.0, v21
	v_floor_f32_e32 v23, v23
	v_cvt_pk_u8_f32 v21, v21, 0, 0
	v_max_f32_e32 v23, 1.0, v23
	v_cvt_pk_u8_f32 v21, v23, 1, v21
	v_fma_f32 v23, v25, s66, 0.5
	v_add_f32_e32 v25, 1.0, v82
	v_fma_f32 v22, v22, s66, 0.5
	v_rcp_f32_e32 v25, v25
	v_exp_f32_e32 v82, v84
	v_floor_f32_e32 v22, v22
	v_max_f32_e32 v22, 1.0, v22
	v_floor_f32_e32 v23, v23
	v_cvt_pk_u8_f32 v22, v22, 0, 0
	v_max_f32_e32 v23, 1.0, v23
	v_cvt_pk_u8_f32 v22, v23, 1, v22
	v_fma_f32 v23, v25, s66, 0.5
	v_add_f32_e32 v25, 1.0, v82
	v_rcp_f32_e32 v25, v25
	v_exp_f32_e32 v82, v89
	v_floor_f32_e32 v23, v23
	v_max_f32_e32 v23, 1.0, v23
	v_cvt_pk_u8_f32 v21, v23, 2, v21
	v_fma_f32 v23, v25, s66, 0.5
	v_add_f32_e32 v25, 1.0, v82
	v_rcp_f32_e32 v25, v25
	v_exp_f32_e32 v82, v85
	v_floor_f32_e32 v23, v23
	v_max_f32_e32 v23, 1.0, v23
	v_cvt_pk_u8_f32 v23, v23, 2, v22
	v_fma_f32 v22, v25, s66, 0.5
	v_add_f32_e32 v25, 1.0, v82
	v_rcp_f32_e32 v25, v25
	v_floor_f32_e32 v22, v22
	v_or_b32_e32 v24, 48, v20
	v_max_f32_e32 v22, 1.0, v22
	v_cvt_pk_u8_f32 v22, v22, 3, v21
	v_fma_f32 v21, v25, s66, 0.5
	v_mad_i64_i32 v[24:25], s[10:11], v24, s25, v[18:19]
	v_floor_f32_e32 v21, v21
	v_lshl_add_u64 v[24:25], v[24:25], 1, s[68:69]
	v_max_f32_e32 v21, 1.0, v21
	v_lshl_add_u64 v[24:25], v[24:25], 0, s[48:49]
	v_cvt_pk_u8_f32 v23, v21, 3, v23
	v_exp_f32_e32 v21, v80
	v_lshl_add_u64 v[24:25], v[24:25], 0, v[0:1]
	v_exp_f32_e32 v78, v78
	v_mov_b32_e32 v236, v22
	v_mov_b32_e32 v237, v23
	v_exp_f32_e32 v23, v81
	v_add_f32_e32 v21, 1.0, v21
	v_add_f32_e32 v22, 1.0, v78
	v_exp_f32_e32 v78, v79
	v_rcp_f32_e32 v21, v21
	v_add_f32_e32 v23, 1.0, v23
	v_rcp_f32_e32 v23, v23
	v_exp_f32_e32 v74, v74
	v_rcp_f32_e32 v22, v22
	v_add_f32_e32 v78, 1.0, v78
	v_fma_f32 v21, v21, s66, 0.5
	v_rcp_f32_e32 v78, v78
	v_floor_f32_e32 v21, v21
	v_fma_f32 v23, v23, s66, 0.5
	v_max_f32_e32 v21, 1.0, v21
	v_floor_f32_e32 v23, v23
	v_add_f32_e32 v74, 1.0, v74
	v_cvt_pk_u8_f32 v21, v21, 0, 0
	v_fma_f32 v22, v22, s66, 0.5
	v_max_f32_e32 v23, 1.0, v23
	v_rcp_f32_e32 v74, v74
	v_exp_f32_e32 v76, v76
	v_floor_f32_e32 v22, v22
	v_cvt_pk_u8_f32 v21, v23, 1, v21
	v_fma_f32 v23, v78, s66, 0.5
	v_max_f32_e32 v22, 1.0, v22
	v_floor_f32_e32 v23, v23
	v_cvt_pk_u8_f32 v22, v22, 0, 0
	v_max_f32_e32 v23, 1.0, v23
	v_cvt_pk_u8_f32 v22, v23, 1, v22
	v_fma_f32 v23, v74, s66, 0.5
	v_add_f32_e32 v74, 1.0, v76
	v_rcp_f32_e32 v74, v74
	v_exp_f32_e32 v75, v75
	v_floor_f32_e32 v23, v23
	v_max_f32_e32 v23, 1.0, v23
	v_cvt_pk_u8_f32 v21, v23, 2, v21
	v_fma_f32 v23, v74, s66, 0.5
	v_add_f32_e32 v74, 1.0, v75
	v_rcp_f32_e32 v74, v74
	v_exp_f32_e32 v75, v77
	v_floor_f32_e32 v23, v23
	v_max_f32_e32 v23, 1.0, v23
	v_cvt_pk_u8_f32 v23, v23, 2, v22
	v_fma_f32 v22, v74, s66, 0.5
	v_add_f32_e32 v74, 1.0, v75
	v_rcp_f32_e32 v74, v74
	v_floor_f32_e32 v22, v22
	v_max_f32_e32 v22, 1.0, v22
	v_cvt_pk_u8_f32 v22, v22, 3, v21
	v_fma_f32 v21, v74, s66, 0.5
	v_floor_f32_e32 v21, v21
	v_max_f32_e32 v21, 1.0, v21
	v_exp_f32_e32 v72, v72
	v_cvt_pk_u8_f32 v23, v21, 3, v23
	v_mov_b32_e32 v238, v22
	v_mov_b32_e32 v239, v23
	global_store_dwordx4 v[24:25], v[236:239], off
	v_exp_f32_e32 v23, v73
	v_add_f32_e32 v21, 1.0, v72
	v_exp_f32_e32 v25, v71
	v_rcp_f32_e32 v21, v21
	v_exp_f32_e32 v22, v70
	v_add_f32_e32 v23, 1.0, v23
	v_rcp_f32_e32 v23, v23
	v_add_f32_e32 v25, 1.0, v25
	v_fma_f32 v21, v21, s66, 0.5
	v_add_f32_e32 v22, 1.0, v22
	v_rcp_f32_e32 v25, v25
	v_exp_f32_e32 v68, v68
	v_floor_f32_e32 v21, v21
	v_rcp_f32_e32 v22, v22
	v_fma_f32 v23, v23, s66, 0.5
	v_max_f32_e32 v21, 1.0, v21
	v_floor_f32_e32 v23, v23
	v_cvt_pk_u8_f32 v21, v21, 0, 0
	v_max_f32_e32 v23, 1.0, v23
	v_cvt_pk_u8_f32 v21, v23, 1, v21
	v_fma_f32 v23, v25, s66, 0.5
	v_add_f32_e32 v25, 1.0, v68
	v_fma_f32 v22, v22, s66, 0.5
	v_rcp_f32_e32 v25, v25
	v_exp_f32_e32 v66, v66
	v_floor_f32_e32 v22, v22
	v_max_f32_e32 v22, 1.0, v22
	v_floor_f32_e32 v23, v23
	v_cvt_pk_u8_f32 v22, v22, 0, 0
	v_max_f32_e32 v23, 1.0, v23
	v_cvt_pk_u8_f32 v22, v23, 1, v22
	v_fma_f32 v23, v25, s66, 0.5
	v_add_f32_e32 v25, 1.0, v66
	v_rcp_f32_e32 v25, v25
	v_exp_f32_e32 v66, v69
	v_floor_f32_e32 v23, v23
	v_max_f32_e32 v23, 1.0, v23
	v_cvt_pk_u8_f32 v21, v23, 2, v21
	v_fma_f32 v23, v25, s66, 0.5
	v_add_f32_e32 v25, 1.0, v66
	v_rcp_f32_e32 v25, v25
	v_exp_f32_e32 v66, v67
	v_floor_f32_e32 v23, v23
	v_max_f32_e32 v23, 1.0, v23
	v_cvt_pk_u8_f32 v23, v23, 2, v22
	v_fma_f32 v22, v25, s66, 0.5
	v_add_f32_e32 v25, 1.0, v66
	v_rcp_f32_e32 v25, v25
	v_floor_f32_e32 v22, v22
	v_add_u32_e32 v24, 0x80, v20
	v_max_f32_e32 v22, 1.0, v22
	v_cvt_pk_u8_f32 v22, v22, 3, v21
	v_fma_f32 v21, v25, s66, 0.5
	v_mad_i64_i32 v[24:25], s[10:11], v24, s25, v[18:19]
	v_floor_f32_e32 v21, v21
	v_lshl_add_u64 v[24:25], v[24:25], 1, s[68:69]
;     __device__ __forceinline__ void operator()(f32x4 (&acc)[2][2][4][2], const Unit& u, int wr, int wc, int fr, int fq) const {
;     ...
;                     if (MODE == 1) {
;                         unsigned g0 = 0u, g1 = 0u;
; #pragma unroll
;                         for (int e = 0; e < 4; ++e) { g0 = __builtin_amdgcn_cvt_pk_u8_f32(fmaxf(floorf(255.f * __builtin_amdgcn_rcpf(1.0f + __builtin_amdgcn_exp2f(v0[e])) + 0.5f), 1.f), e, g0);
;                                                       g1 = __builtin_amdgcn_cvt_pk_u8_f32(fmaxf(floorf(255.f * __builtin_amdgcn_rcpf(1.0f + __builtin_amdgcn_exp2f(v1[e])) + 0.5f), 1.f), e, g1); }
;                         *(u32x2*)((unsigned char*)O + ((size_t)(row0 + ai * HALF + m * 16) * ldc + colt) * 2 + bj * HALF + wc * 32 + 8 * fq) = (u32x2){g0, g1};
	v_max_f32_e32 v21, 1.0, v21
	v_lshl_add_u64 v[24:25], v[24:25], 0, s[48:49]
	v_cvt_pk_u8_f32 v23, v21, 3, v23
	v_exp_f32_e32 v21, v64
	v_lshl_add_u64 v[24:25], v[24:25], 0, v[0:1]
	v_exp_f32_e32 v62, v62
	v_mov_b32_e32 v240, v22
	v_mov_b32_e32 v241, v23
	v_exp_f32_e32 v23, v65
	v_add_f32_e32 v21, 1.0, v21
	v_add_f32_e32 v22, 1.0, v62
	v_exp_f32_e32 v62, v63
	v_rcp_f32_e32 v21, v21
	v_add_f32_e32 v23, 1.0, v23
	v_rcp_f32_e32 v23, v23
	v_exp_f32_e32 v58, v58
	v_rcp_f32_e32 v22, v22
	v_add_f32_e32 v62, 1.0, v62
	v_fma_f32 v21, v21, s66, 0.5
	v_rcp_f32_e32 v62, v62
	v_floor_f32_e32 v21, v21
	v_fma_f32 v23, v23, s66, 0.5
	v_max_f32_e32 v21, 1.0, v21
	v_floor_f32_e32 v23, v23
	v_add_f32_e32 v58, 1.0, v58
	v_cvt_pk_u8_f32 v21, v21, 0, 0
	v_fma_f32 v22, v22, s66, 0.5
	v_max_f32_e32 v23, 1.0, v23
	v_rcp_f32_e32 v58, v58
	v_exp_f32_e32 v60, v60
	v_floor_f32_e32 v22, v22
	v_cvt_pk_u8_f32 v21, v23, 1, v21
	v_fma_f32 v23, v62, s66, 0.5
	v_max_f32_e32 v22, 1.0, v22
	v_floor_f32_e32 v23, v23
	v_cvt_pk_u8_f32 v22, v22, 0, 0
	v_max_f32_e32 v23, 1.0, v23
	v_cvt_pk_u8_f32 v22, v23, 1, v22
	v_fma_f32 v23, v58, s66, 0.5
	v_add_f32_e32 v58, 1.0, v60
	v_rcp_f32_e32 v58, v58
	v_exp_f32_e32 v59, v59
	v_floor_f32_e32 v23, v23
	v_max_f32_e32 v23, 1.0, v23
	v_cvt_pk_u8_f32 v21, v23, 2, v21
	v_fma_f32 v23, v58, s66, 0.5
	v_add_f32_e32 v58, 1.0, v59
	v_rcp_f32_e32 v58, v58
	v_exp_f32_e32 v59, v61
	v_floor_f32_e32 v23, v23
	v_max_f32_e32 v23, 1.0, v23
	v_cvt_pk_u8_f32 v23, v23, 2, v22
	v_fma_f32 v22, v58, s66, 0.5
	v_add_f32_e32 v58, 1.0, v59
	v_rcp_f32_e32 v58, v58
	v_floor_f32_e32 v22, v22
	v_max_f32_e32 v22, 1.0, v22
	v_cvt_pk_u8_f32 v22, v22, 3, v21
	v_fma_f32 v21, v58, s66, 0.5
	v_floor_f32_e32 v21, v21
	v_max_f32_e32 v21, 1.0, v21
	v_exp_f32_e32 v54, v54
	v_cvt_pk_u8_f32 v23, v21, 3, v23
	v_mov_b32_e32 v242, v22
	v_mov_b32_e32 v243, v23
	global_store_dwordx4 v[24:25], v[240:243], off
	v_exp_f32_e32 v23, v55
	v_add_f32_e32 v21, 1.0, v54
	v_exp_f32_e32 v25, v51
	v_rcp_f32_e32 v21, v21
	v_exp_f32_e32 v22, v50
	v_add_f32_e32 v23, 1.0, v23
	v_rcp_f32_e32 v23, v23
	v_add_f32_e32 v25, 1.0, v25
	v_fma_f32 v21, v21, s66, 0.5
	v_add_f32_e32 v22, 1.0, v22
	v_rcp_f32_e32 v25, v25
	v_exp_f32_e32 v50, v56
	v_floor_f32_e32 v21, v21
	v_rcp_f32_e32 v22, v22
	v_fma_f32 v23, v23, s66, 0.5
	v_max_f32_e32 v21, 1.0, v21
	v_floor_f32_e32 v23, v23
	v_cvt_pk_u8_f32 v21, v21, 0, 0
	v_max_f32_e32 v23, 1.0, v23
	v_cvt_pk_u8_f32 v21, v23, 1, v21
	v_fma_f32 v23, v25, s66, 0.5
	v_add_f32_e32 v25, 1.0, v50
	v_fma_f32 v22, v22, s66, 0.5
	v_rcp_f32_e32 v25, v25
	v_exp_f32_e32 v50, v52
	v_floor_f32_e32 v22, v22
	v_max_f32_e32 v22, 1.0, v22
	v_floor_f32_e32 v23, v23
	v_cvt_pk_u8_f32 v22, v22, 0, 0
	v_max_f32_e32 v23, 1.0, v23
	v_cvt_pk_u8_f32 v22, v23, 1, v22
	v_fma_f32 v23, v25, s66, 0.5
	v_add_f32_e32 v25, 1.0, v50
	v_rcp_f32_e32 v25, v25
	v_exp_f32_e32 v50, v57
	v_floor_f32_e32 v23, v23
	v_max_f32_e32 v23, 1.0, v23
	v_cvt_pk_u8_f32 v21, v23, 2, v21
	v_fma_f32 v23, v25, s66, 0.5
	v_add_f32_e32 v25, 1.0, v50
	v_rcp_f32_e32 v25, v25
	v_exp_f32_e32 v50, v53
	v_floor_f32_e32 v23, v23
	v_max_f32_e32 v23, 1.0, v23
	v_cvt_pk_u8_f32 v23, v23, 2, v22
	v_fma_f32 v22, v25, s66, 0.5
	v_add_f32_e32 v25, 1.0, v50
	v_rcp_f32_e32 v25, v25
	v_floor_f32_e32 v22, v22
	v_add_u32_e32 v24, 0x90, v20
	v_max_f32_e32 v22, 1.0, v22
	v_cvt_pk_u8_f32 v22, v22, 3, v21
	v_fma_f32 v21, v25, s66, 0.5
	v_mad_i64_i32 v[24:25], s[10:11], v24, s25, v[18:19]
	v_floor_f32_e32 v21, v21
	v_lshl_add_u64 v[24:25], v[24:25], 1, s[68:69]
	v_max_f32_e32 v21, 1.0, v21
	v_lshl_add_u64 v[24:25], v[24:25], 0, s[48:49]
	v_cvt_pk_u8_f32 v23, v21, 3, v23
	v_exp_f32_e32 v21, v48
	v_lshl_add_u64 v[24:25], v[24:25], 0, v[0:1]
	v_exp_f32_e32 v46, v46
	v_mov_b32_e32 v236, v22
	v_mov_b32_e32 v237, v23
	v_exp_f32_e32 v23, v49
	v_add_f32_e32 v21, 1.0, v21
	v_add_f32_e32 v22, 1.0, v46
	v_exp_f32_e32 v46, v47
	v_rcp_f32_e32 v21, v21
	v_add_f32_e32 v23, 1.0, v23
	v_rcp_f32_e32 v23, v23
	v_exp_f32_e32 v42, v42
	v_rcp_f32_e32 v22, v22
	v_add_f32_e32 v46, 1.0, v46
	v_fma_f32 v21, v21, s66, 0.5
	v_rcp_f32_e32 v46, v46
	v_floor_f32_e32 v21, v21
	v_fma_f32 v23, v23, s66, 0.5
	v_max_f32_e32 v21, 1.0, v21
	v_floor_f32_e32 v23, v23
	v_add_f32_e32 v42, 1.0, v42
	v_cvt_pk_u8_f32 v21, v21, 0, 0
	v_fma_f32 v22, v22, s66, 0.5
	v_max_f32_e32 v23, 1.0, v23
	v_rcp_f32_e32 v42, v42
	v_exp_f32_e32 v44, v44
	v_floor_f32_e32 v22, v22
	v_cvt_pk_u8_f32 v21, v23, 1, v21
	v_fma_f32 v23, v46, s66, 0.5
	v_max_f32_e32 v22, 1.0, v22
	v_floor_f32_e32 v23, v23
	v_cvt_pk_u8_f32 v22, v22, 0, 0
	v_max_f32_e32 v23, 1.0, v23
	v_cvt_pk_u8_f32 v22, v23, 1, v22
	v_fma_f32 v23, v42, s66, 0.5
	v_add_f32_e32 v42, 1.0, v44
	v_rcp_f32_e32 v42, v42
	v_exp_f32_e32 v43, v43
	v_floor_f32_e32 v23, v23
	v_max_f32_e32 v23, 1.0, v23
	v_cvt_pk_u8_f32 v21, v23, 2, v21
	v_fma_f32 v23, v42, s66, 0.5
	v_add_f32_e32 v42, 1.0, v43
	v_rcp_f32_e32 v42, v42
	v_exp_f32_e32 v43, v45
	v_floor_f32_e32 v23, v23
	v_max_f32_e32 v23, 1.0, v23
	v_cvt_pk_u8_f32 v23, v23, 2, v22
	v_fma_f32 v22, v42, s66, 0.5
	v_add_f32_e32 v42, 1.0, v43
	v_rcp_f32_e32 v42, v42
	v_floor_f32_e32 v22, v22
	v_max_f32_e32 v22, 1.0, v22
	v_cvt_pk_u8_f32 v22, v22, 3, v21
	v_fma_f32 v21, v42, s66, 0.5
	v_floor_f32_e32 v21, v21
	v_max_f32_e32 v21, 1.0, v21
	v_exp_f32_e32 v38, v38
	v_cvt_pk_u8_f32 v23, v21, 3, v23
	v_mov_b32_e32 v238, v22
	v_mov_b32_e32 v239, v23
	global_store_dwordx4 v[24:25], v[236:239], off
	v_exp_f32_e32 v23, v39
	v_add_f32_e32 v21, 1.0, v38
	v_exp_f32_e32 v25, v35
	v_rcp_f32_e32 v21, v21
	v_exp_f32_e32 v22, v34
	v_add_f32_e32 v23, 1.0, v23
	v_rcp_f32_e32 v23, v23
	v_add_f32_e32 v25, 1.0, v25
	v_fma_f32 v21, v21, s66, 0.5
;     __device__ __forceinline__ void operator()(f32x4 (&acc)[2][2][4][2], const Unit& u, int wr, int wc, int fr, int fq) const {
;     ...
;                     if (MODE == 1) {
;                         unsigned g0 = 0u, g1 = 0u;
; #pragma unroll
;                         for (int e = 0; e < 4; ++e) { g0 = __builtin_amdgcn_cvt_pk_u8_f32(fmaxf(floorf(255.f * __builtin_amdgcn_rcpf(1.0f + __builtin_amdgcn_exp2f(v0[e])) + 0.5f), 1.f), e, g0);
;                                                       g1 = __builtin_amdgcn_cvt_pk_u8_f32(fmaxf(floorf(255.f * __builtin_amdgcn_rcpf(1.0f + __builtin_amdgcn_exp2f(v1[e])) + 0.5f), 1.f), e, g1); }
;                         *(u32x2*)((unsigned char*)O + ((size_t)(row0 + ai * HALF + m * 16) * ldc + colt) * 2 + bj * HALF + wc * 32 + 8 * fq) = (u32x2){g0, g1};
	v_add_f32_e32 v22, 1.0, v22
	v_rcp_f32_e32 v25, v25
	v_exp_f32_e32 v34, v40
	v_floor_f32_e32 v21, v21
	v_rcp_f32_e32 v22, v22
	v_fma_f32 v23, v23, s66, 0.5
	v_max_f32_e32 v21, 1.0, v21
	v_floor_f32_e32 v23, v23
	v_cvt_pk_u8_f32 v21, v21, 0, 0
	v_max_f32_e32 v23, 1.0, v23
	v_cvt_pk_u8_f32 v21, v23, 1, v21
	v_fma_f32 v23, v25, s66, 0.5
	v_add_f32_e32 v25, 1.0, v34
	v_fma_f32 v22, v22, s66, 0.5
	v_rcp_f32_e32 v25, v25
	v_exp_f32_e32 v34, v36
	v_floor_f32_e32 v22, v22
	v_max_f32_e32 v22, 1.0, v22
	v_floor_f32_e32 v23, v23
	v_exp_f32_e32 v14, v14
	v_cvt_pk_u8_f32 v22, v22, 0, 0
	v_max_f32_e32 v23, 1.0, v23
	v_exp_f32_e32 v15, v15
	v_cvt_pk_u8_f32 v22, v23, 1, v22
	v_fma_f32 v23, v25, s66, 0.5
	v_add_f32_e32 v25, 1.0, v34
	v_exp_f32_e32 v16, v16
	v_exp_f32_e32 v10, v10
	v_rcp_f32_e32 v25, v25
	v_exp_f32_e32 v34, v41
	v_exp_f32_e32 v17, v17
	v_add_f32_e32 v14, 1.0, v14
	v_exp_f32_e32 v12, v12
	v_floor_f32_e32 v23, v23
	v_rcp_f32_e32 v14, v14
	v_add_f32_e32 v15, 1.0, v15
	v_exp_f32_e32 v13, v13
	v_max_f32_e32 v23, 1.0, v23
	v_add_f32_e32 v16, 1.0, v16
	v_rcp_f32_e32 v15, v15
	v_add_f32_e32 v10, 1.0, v10
	v_cvt_pk_u8_f32 v21, v23, 2, v21
	v_fma_f32 v23, v25, s66, 0.5
	v_add_f32_e32 v25, 1.0, v34
	v_rcp_f32_e32 v16, v16
	v_add_f32_e32 v17, 1.0, v17
	v_rcp_f32_e32 v10, v10
	v_rcp_f32_e32 v25, v25
	v_exp_f32_e32 v34, v37
	v_rcp_f32_e32 v17, v17
	v_add_f32_e32 v12, 1.0, v12
	v_fma_f32 v14, v14, s66, 0.5
	v_rcp_f32_e32 v12, v12
	v_add_f32_e32 v13, 1.0, v13
	v_floor_f32_e32 v23, v23
	v_floor_f32_e32 v14, v14
	v_fma_f32 v15, v15, s66, 0.5
	v_rcp_f32_e32 v13, v13
	v_max_f32_e32 v23, 1.0, v23
	v_fma_f32 v16, v16, s66, 0.5
	v_max_f32_e32 v14, 1.0, v14
	v_floor_f32_e32 v15, v15
	v_fma_f32 v10, v10, s66, 0.5
	v_exp_f32_e32 v6, v6
	v_cvt_pk_u8_f32 v23, v23, 2, v22
	v_fma_f32 v22, v25, s66, 0.5
	v_add_f32_e32 v25, 1.0, v34
	v_floor_f32_e32 v16, v16
	v_cvt_pk_u8_f32 v14, v14, 0, 0
	v_fma_f32 v17, v17, s66, 0.5
	v_max_f32_e32 v15, 1.0, v15
	v_floor_f32_e32 v10, v10
	v_rcp_f32_e32 v25, v25
	v_max_f32_e32 v16, 1.0, v16
	v_floor_f32_e32 v17, v17
	v_cvt_pk_u8_f32 v14, v15, 1, v14
	v_fma_f32 v12, v12, s66, 0.5
	v_max_f32_e32 v10, 1.0, v10
	v_cvt_pk_u8_f32 v16, v16, 0, 0
	v_max_f32_e32 v17, 1.0, v17
	v_floor_f32_e32 v12, v12
	v_cvt_pk_u8_f32 v14, v10, 2, v14
	v_fma_f32 v10, v13, s66, 0.5
	v_floor_f32_e32 v22, v22
	v_cvt_pk_u8_f32 v16, v17, 1, v16
	v_max_f32_e32 v12, 1.0, v12
	v_floor_f32_e32 v10, v10
	v_add_f32_e32 v6, 1.0, v6
	v_add_u32_e32 v24, 0xa0, v20
	v_max_f32_e32 v22, 1.0, v22
	v_add_u32_e32 v20, 0xb0, v20
	v_cvt_pk_u8_f32 v12, v12, 2, v16
	v_max_f32_e32 v10, 1.0, v10
	v_rcp_f32_e32 v6, v6
	v_cvt_pk_u8_f32 v22, v22, 3, v21
	v_fma_f32 v21, v25, s66, 0.5
	v_mad_i64_i32 v[24:25], s[10:11], v24, s25, v[18:19]
	v_cvt_pk_u8_f32 v10, v10, 3, v12
	v_mad_i64_i32 v[12:13], s[10:11], v20, s25, v[18:19]
	v_floor_f32_e32 v21, v21
	v_lshl_add_u64 v[24:25], v[24:25], 1, s[68:69]
	v_lshl_add_u64 v[12:13], v[12:13], 1, s[68:69]
	v_max_f32_e32 v21, 1.0, v21
	v_lshl_add_u64 v[24:25], v[24:25], 0, s[48:49]
	v_lshl_add_u64 v[12:13], v[12:13], 0, s[48:49]
	v_cvt_pk_u8_f32 v23, v21, 3, v23
	v_exp_f32_e32 v21, v32
	v_lshl_add_u64 v[24:25], v[24:25], 0, v[0:1]
	v_exp_f32_e32 v30, v30
	v_lshl_add_u64 v[12:13], v[12:13], 0, v[0:1]
	v_exp_f32_e32 v0, v2
	v_fma_f32 v2, v6, s66, 0.5
	v_exp_f32_e32 v6, v7
	v_mov_b32_e32 v240, v22
	v_mov_b32_e32 v241, v23
	v_exp_f32_e32 v23, v33
	v_add_f32_e32 v21, 1.0, v21
	v_add_f32_e32 v22, 1.0, v30
	v_exp_f32_e32 v30, v31
	v_add_f32_e32 v6, 1.0, v6
	v_rcp_f32_e32 v21, v21
	v_add_f32_e32 v23, 1.0, v23
	v_rcp_f32_e32 v6, v6
	v_exp_f32_e32 v3, v3
	v_rcp_f32_e32 v23, v23
	v_exp_f32_e32 v26, v26
	v_rcp_f32_e32 v22, v22
	v_add_f32_e32 v30, 1.0, v30
	v_add_f32_e32 v0, 1.0, v0
	v_exp_f32_e32 v7, v8
	v_fma_f32 v21, v21, s66, 0.5
	v_rcp_f32_e32 v30, v30
	v_floor_f32_e32 v2, v2
	v_rcp_f32_e32 v0, v0
	v_fma_f32 v6, v6, s66, 0.5
	v_add_f32_e32 v3, 1.0, v3
	v_floor_f32_e32 v21, v21
	v_fma_f32 v23, v23, s66, 0.5
	v_max_f32_e32 v2, 1.0, v2
	v_floor_f32_e32 v6, v6
	v_rcp_f32_e32 v3, v3
	v_max_f32_e32 v21, 1.0, v21
	v_floor_f32_e32 v23, v23
	v_add_f32_e32 v26, 1.0, v26
	v_cvt_pk_u8_f32 v2, v2, 0, 0
	v_max_f32_e32 v6, 1.0, v6
	v_cvt_pk_u8_f32 v21, v21, 0, 0
	v_fma_f32 v22, v22, s66, 0.5
	v_max_f32_e32 v23, 1.0, v23
	v_rcp_f32_e32 v26, v26
	v_exp_f32_e32 v28, v28
	v_cvt_pk_u8_f32 v2, v6, 1, v2
	v_add_f32_e32 v6, 1.0, v7
	v_exp_f32_e32 v4, v4
	v_floor_f32_e32 v22, v22
	v_cvt_pk_u8_f32 v21, v23, 1, v21
	v_fma_f32 v23, v30, s66, 0.5
	v_fma_f32 v0, v0, s66, 0.5
	v_rcp_f32_e32 v6, v6
	v_max_f32_e32 v22, 1.0, v22
	v_floor_f32_e32 v23, v23
	v_floor_f32_e32 v0, v0
	v_fma_f32 v3, v3, s66, 0.5
	v_cvt_pk_u8_f32 v22, v22, 0, 0
	v_max_f32_e32 v23, 1.0, v23
	v_max_f32_e32 v0, 1.0, v0
	v_floor_f32_e32 v3, v3
	v_cvt_pk_u8_f32 v22, v23, 1, v22
	v_fma_f32 v23, v26, s66, 0.5
	v_add_f32_e32 v26, 1.0, v28
	v_cvt_pk_u8_f32 v0, v0, 0, 0
	v_max_f32_e32 v3, 1.0, v3
	v_add_f32_e32 v4, 1.0, v4
	v_rcp_f32_e32 v26, v26
	v_exp_f32_e32 v27, v27
	v_cvt_pk_u8_f32 v0, v3, 1, v0
	v_fma_f32 v3, v6, s66, 0.5
	v_rcp_f32_e32 v4, v4
	v_exp_f32_e32 v6, v9
	v_floor_f32_e32 v23, v23
	v_floor_f32_e32 v3, v3
	v_max_f32_e32 v23, 1.0, v23
	v_max_f32_e32 v3, 1.0, v3
	v_cvt_pk_u8_f32 v21, v23, 2, v21
	v_fma_f32 v23, v26, s66, 0.5
	v_add_f32_e32 v26, 1.0, v27
	v_cvt_pk_u8_f32 v2, v3, 2, v2
	v_fma_f32 v3, v4, s66, 0.5
	v_add_f32_e32 v4, 1.0, v6
	v_rcp_f32_e32 v26, v26
	v_exp_f32_e32 v27, v29
	v_exp_f32_e32 v11, v11
	v_rcp_f32_e32 v4, v4
	v_exp_f32_e32 v5, v5
	v_floor_f32_e32 v23, v23
	v_floor_f32_e32 v3, v3
	v_max_f32_e32 v23, 1.0, v23
	v_max_f32_e32 v3, 1.0, v3
	v_cvt_pk_u8_f32 v23, v23, 2, v22
	v_fma_f32 v22, v26, s66, 0.5
	v_add_f32_e32 v26, 1.0, v27
	v_add_f32_e32 v11, 1.0, v11
	v_cvt_pk_u8_f32 v0, v3, 2, v0
	v_fma_f32 v3, v4, s66, 0.5
	v_add_f32_e32 v4, 1.0, v5
	v_rcp_f32_e32 v26, v26
	v_rcp_f32_e32 v11, v11
	v_rcp_f32_e32 v4, v4
	v_floor_f32_e32 v22, v22
	v_floor_f32_e32 v3, v3
	v_max_f32_e32 v22, 1.0, v22
	v_max_f32_e32 v3, 1.0, v3
	v_cvt_pk_u8_f32 v22, v22, 3, v21
	v_fma_f32 v21, v26, s66, 0.5
	v_fma_f32 v11, v11, s66, 0.5
	v_cvt_pk_u8_f32 v2, v3, 3, v2
	v_fma_f32 v3, v4, s66, 0.5
	v_floor_f32_e32 v21, v21
	v_floor_f32_e32 v11, v11
	v_floor_f32_e32 v3, v3
	v_max_f32_e32 v21, 1.0, v21
	v_max_f32_e32 v11, 1.0, v11
	v_max_f32_e32 v3, 1.0, v3
	v_cvt_pk_u8_f32 v23, v21, 3, v23
	v_cvt_pk_u8_f32 v11, v11, 3, v14
	v_cvt_pk_u8_f32 v3, v3, 3, v0
	s_andn2_b64 vcc, exec, s[40:41]
	s_mov_b64 s[10:11], -1
	v_mov_b32_e32 v242, v22
	v_mov_b32_e32 v243, v23
	global_store_dwordx4 v[24:25], v[240:243], off
	v_mov_b32_e32 v236, v10
	v_mov_b32_e32 v237, v11
	v_mov_b32_e32 v238, v2
	v_mov_b32_e32 v239, v3
	global_store_dwordx4 v[12:13], v[236:239], off
	s_cbranch_vccnz .LBB0_673
	s_andn2_b64 vcc, exec, s[0:1]
	s_cbranch_vccnz .LBB0_672
	s_barrier
	s_branch .LBB0_672
